# GLA matrix-core loops fed from registers: each wave loads its own q/k/v operand fragments from global memory (4 blocks ahead), no LDS staging; next block's operand preparation and previous block's out
# baseline (speedup 1.0000x reference)
.LBB0_242:
	s_andn2_b64 vcc, exec, s[8:9]
	s_cbranch_vccnz .LBB0_184
	s_lshr_b32 s20, s1, 2
	s_and_b32 s21, s1, 3
	s_lshr_b32 s14, s20, 4
	s_xor_b32 s14, s14, 1
	s_bfe_u32 s22, s20, 0x20002
	s_and_b32 s23, s20, 3
	s_mul_i32 s24, s14, 6144
	s_lshl_b32 s25, s23, 8
	s_add_u32 s24, s24, s25
	s_addk_i32 s24, 3072
	s_mul_i32 s25, s22, 0x6800000
	s_add_u32 s24, s24, s25
	s_add_u32 s8, s78, 0x15e00000
	s_addc_u32 s9, s79, 0
	s_add_u32 s8, s8, s24
	s_addc_u32 s9, s9, 0
	s_lshl_b32 s24, s14, 11
	s_lshl_b32 s25, s23, 8
	s_add_u32 s24, s24, s25
	s_lshl_b32 s25, s21, 6
	s_add_u32 s24, s24, s25
	s_addk_i32 s24, 1024
	s_lshl_b32 s25, s22, 25
	s_add_u32 s24, s24, s25
	s_add_u32 s10, s78, 0x2fe00000
	s_addc_u32 s11, s79, 0
	s_add_u32 s10, s10, s24
	s_addc_u32 s11, s11, 0
	s_lshl_b32 s24, s14, 23
	s_lshl_b32 s25, s22, 21
	s_add_u32 s24, s24, s25
	s_lshl_b32 s25, s23, 6
	s_add_u32 s24, s24, s25
	s_lshl_b32 s25, s21, 4
	s_add_u32 s24, s24, s25
	s_add_u32 s12, s78, 0x3ae90000
	s_addc_u32 s13, s79, 0
	s_add_u32 s12, s12, s24
	s_addc_u32 s13, s13, 0
	v_lshrrev_b32_e32 v155, 5, v163
	v_and_b32_e32 v156, 31, v163
	v_and_b32_e32 v157, 15, v163
	v_bfe_u32 v158, v163, 4, 2
	v_lshrrev_b32_e32 v159, 6, v163
	v_mul_u32_u24_e32 v130, 0x3400, v157
	v_lshl_add_u32 v130, v159, 5, v130
	v_lshl_add_u32 v130, v158, 3, v130
	s_lshl_b32 s24, s21, 6
	s_addk_i32 s24, 2048
	v_mul_u32_u24_e32 v131, 0x3400, v158
	v_lshl_add_u32 v131, v157, 2, v131
	v_add_u32_e32 v131, s24, v131
	v_add_u32_e32 v132, 0xd000, v131
	v_add_u32_e32 v133, 0x1a000, v131
	v_add_u32_e32 v134, 0x27000, v131
	v_lshlrev_b32_e32 v135, 12, v155
	v_lshl_add_u32 v135, v156, 1, v135
	v_lshlrev_b32_e32 v139, 8, v155
	v_mul_u32_u24_e32 v160, 1040, v155
	v_lshl_add_u32 v160, v156, 2, v160
	v_add_u32_e32 v148, 0x10000, v160
	v_add_u32_e32 v149, 0x14400, v160
	v_mul_u32_u24_e32 v160, 1040, v157
	v_lshl_add_u32 v160, v159, 7, v160
	v_lshl_add_u32 v160, v158, 5, v160
	v_add_u32_e32 v150, 0x10000, v160
	v_add_u32_e32 v152, 0x14400, v160
	v_mul_u32_u24_e32 v160, 1280, v159
	v_add_u32_e32 v160, 0x19000, v160
	v_mul_u32_u24_e32 v153, 80, v157
	v_add_u32_e32 v153, v153, v160
	v_lshl_add_u32 v153, v158, 4, v153
	v_mul_u32_u24_e32 v154, 80, v158
	v_add_u32_e32 v154, v154, v160
	v_lshl_add_u32 v154, v157, 2, v154
	s_sub_u32 s24, 122, s23
	s_lshl_b32 s24, s24, 23
	v_mov_b32_e32 v195, s24
	v_sub_f32_e32 v195, 1.0, v195
	v_mov_b32_e32 v0, 0
	v_mov_b32_e32 v1, 0
	v_mov_b32_e32 v2, 0
	v_mov_b32_e32 v3, 0
	v_mov_b32_e32 v4, 0
	v_mov_b32_e32 v5, 0
	v_mov_b32_e32 v6, 0
	v_mov_b32_e32 v7, 0
	v_mov_b32_e32 v40, 0
	v_mov_b32_e32 v41, 0
	v_mov_b32_e32 v42, 0
	v_mov_b32_e32 v43, 0
	v_mov_b32_e32 v52, 0
	v_mov_b32_e32 v53, 0
	v_mov_b32_e32 v54, 0
	v_mov_b32_e32 v55, 0
	v_mov_b32_e32 v56, 0
	v_mov_b32_e32 v57, 0
	v_mov_b32_e32 v58, 0
	v_mov_b32_e32 v59, 0
	s_mov_b32 s18, 1
	s_mov_b32 s19, 1
	s_movk_i32 s15, 512
	global_load_dwordx2 v[100:101], v130, s[8:9]
	global_load_dwordx2 v[102:103], v130, s[8:9] offset:1024
	global_load_dword v104, v131, s[8:9]
	global_load_dword v105, v132, s[8:9]
	global_load_dword v106, v133, s[8:9]
	global_load_dword v107, v134, s[8:9]
	s_add_u32 s8, s8, 0x34000
	s_addc_u32 s9, s9, 0
	s_cmp_eq_u32 s14, 0
	s_cbranch_scc1 .Lgla_ret_setup
	v_lshl_add_u32 v127, v158, 2, 0
	v_cmp_le_u32_e32 vcc, v127, v157
	s_nop 1
	v_cndmask_b32_e64 v74, 0, 1.0, vcc
	v_lshl_add_u32 v127, v158, 2, 1
	v_cmp_le_u32_e32 vcc, v127, v157
	s_nop 1
	v_cndmask_b32_e64 v75, 0, 1.0, vcc
	v_lshl_add_u32 v127, v158, 2, 2
	v_cmp_le_u32_e32 vcc, v127, v157
	s_nop 1
	v_cndmask_b32_e64 v76, 0, 1.0, vcc
	v_lshl_add_u32 v127, v158, 2, 3
	v_cmp_le_u32_e32 vcc, v127, v157
	s_nop 1
	v_cndmask_b32_e64 v77, 0, 1.0, vcc
	s_waitcnt vmcnt(0)
	v_lshlrev_b32_e32 v20, 16, v100
	v_and_b32_e32 v21, s69, v100
	v_lshlrev_b32_e32 v22, 16, v101
	v_and_b32_e32 v23, s69, v101
	v_lshlrev_b32_e32 v24, 16, v102
	v_and_b32_e32 v25, s69, v102
	v_lshlrev_b32_e32 v26, 16, v103
	v_and_b32_e32 v27, s69, v103
	v_lshlrev_b32_e32 v44, 16, v104
	v_and_b32_e32 v45, s69, v104
	v_lshlrev_b32_e32 v46, 16, v105
	v_and_b32_e32 v47, s69, v105
	v_lshlrev_b32_e32 v48, 16, v106
	v_and_b32_e32 v49, s69, v106
	v_lshlrev_b32_e32 v50, 16, v107
	v_and_b32_e32 v51, s69, v107
	v_mul_f32_e32 v24, 0x3fb8aa3b, v24
	v_mul_f32_e32 v25, 0x3fb8aa3b, v25
	v_mul_f32_e32 v26, 0x3fb8aa3b, v26
	v_mul_f32_e32 v27, 0x3fb8aa3b, v27
	v_add_f32_dpp v80, v24, v24 row_shl:1 row_mask:0xf bank_mask:0xf bound_ctrl:0
	v_add_f32_dpp v81, v25, v25 row_shl:1 row_mask:0xf bank_mask:0xf bound_ctrl:0
	v_add_f32_dpp v82, v26, v26 row_shl:1 row_mask:0xf bank_mask:0xf bound_ctrl:0
	v_add_f32_dpp v83, v27, v27 row_shl:1 row_mask:0xf bank_mask:0xf bound_ctrl:0
	v_add_f32_dpp v80, v80, v80 row_shl:2 row_mask:0xf bank_mask:0xf bound_ctrl:0
	v_add_f32_dpp v81, v81, v81 row_shl:2 row_mask:0xf bank_mask:0xf bound_ctrl:0
	v_add_f32_dpp v82, v82, v82 row_shl:2 row_mask:0xf bank_mask:0xf bound_ctrl:0
	v_add_f32_dpp v83, v83, v83 row_shl:2 row_mask:0xf bank_mask:0xf bound_ctrl:0
	v_add_f32_dpp v80, v80, v80 row_shl:4 row_mask:0xf bank_mask:0xf bound_ctrl:0
	v_add_f32_dpp v81, v81, v81 row_shl:4 row_mask:0xf bank_mask:0xf bound_ctrl:0
	v_add_f32_dpp v82, v82, v82 row_shl:4 row_mask:0xf bank_mask:0xf bound_ctrl:0
	v_add_f32_dpp v83, v83, v83 row_shl:4 row_mask:0xf bank_mask:0xf bound_ctrl:0
	v_add_f32_dpp v80, v80, v80 row_shl:8 row_mask:0xf bank_mask:0xf bound_ctrl:0
	v_add_f32_dpp v81, v81, v81 row_shl:8 row_mask:0xf bank_mask:0xf bound_ctrl:0
	v_add_f32_dpp v82, v82, v82 row_shl:8 row_mask:0xf bank_mask:0xf bound_ctrl:0
	v_add_f32_dpp v83, v83, v83 row_shl:8 row_mask:0xf bank_mask:0xf bound_ctrl:0
	v_exp_f32_e32 v84, v24
	v_exp_f32_e32 v85, v25
	v_exp_f32_e32 v86, v26
	v_exp_f32_e32 v87, v27
	ds_swizzle_b32 v96, v80 offset:swizzle(BITMASK_PERM,"p0000")
	ds_swizzle_b32 v97, v81 offset:swizzle(BITMASK_PERM,"p0000")
	ds_swizzle_b32 v98, v82 offset:swizzle(BITMASK_PERM,"p0000")
	ds_swizzle_b32 v99, v83 offset:swizzle(BITMASK_PERM,"p0000")
	v_sub_f32_e32 v88, v80, v24
	v_sub_f32_e32 v89, v81, v25
	v_sub_f32_e32 v90, v82, v26
	v_sub_f32_e32 v91, v83, v27
	v_max_f32_e32 v88, 0xc2fc0000, v88
	v_max_f32_e32 v89, 0xc2fc0000, v89
	v_max_f32_e32 v90, 0xc2fc0000, v90
	v_max_f32_e32 v91, 0xc2fc0000, v91
	v_sub_f32_e32 v84, 1.0, v84
	v_sub_f32_e32 v85, 1.0, v85
	v_sub_f32_e32 v86, 1.0, v86
	v_sub_f32_e32 v87, 1.0, v87
	v_exp_f32_e64 v92, -v88
	v_exp_f32_e64 v93, -v89
	v_exp_f32_e64 v94, -v90
	v_exp_f32_e64 v95, -v91
	v_exp_f32_e32 v88, v88
	v_exp_f32_e32 v89, v89
	v_exp_f32_e32 v90, v90
	v_exp_f32_e32 v91, v91
	s_waitcnt lgkmcnt(0)
	v_exp_f32_e32 v60, v96
	v_exp_f32_e32 v61, v97
	v_exp_f32_e32 v62, v98
	v_exp_f32_e32 v63, v99
	v_mul_f32_e32 v24, v84, v88
	v_mul_f32_e32 v25, v85, v89
	v_mul_f32_e32 v26, v86, v90
	v_mul_f32_e32 v27, v87, v91
	v_mul_f32_e32 v20, v20, v92
	v_mul_f32_e32 v21, v21, v93
	v_mul_f32_e32 v22, v22, v94
	v_mul_f32_e32 v23, v23, v95
	ds_write_b128 v153, v[24:27]
	ds_read_b32 v36, v154 offset:0
	ds_read_b32 v37, v154 offset:320
	ds_read_b32 v38, v154 offset:640
	ds_read_b32 v39, v154 offset:960
	s_waitcnt lgkmcnt(0)
	global_load_dword v124, v130, s[8:9]
	global_load_dword v124, v130, s[8:9]
	global_load_dwordx2 v[108:109], v130, s[8:9]
	global_load_dwordx2 v[110:111], v130, s[8:9] offset:1024
	global_load_dword v112, v131, s[8:9]
	global_load_dword v113, v132, s[8:9]
	global_load_dword v114, v133, s[8:9]
	global_load_dword v115, v134, s[8:9]
	s_add_u32 s8, s8, 0x34000
	s_addc_u32 s9, s9, 0
	global_load_dword v124, v130, s[8:9]
	global_load_dword v124, v130, s[8:9]
	global_load_dwordx2 v[116:117], v130, s[8:9]
	global_load_dwordx2 v[118:119], v130, s[8:9] offset:1024
	global_load_dword v120, v131, s[8:9]
	global_load_dword v121, v132, s[8:9]
	global_load_dword v122, v133, s[8:9]
	global_load_dword v123, v134, s[8:9]
	s_add_u32 s8, s8, 0x34000
	s_addc_u32 s9, s9, 0
	global_load_dword v124, v130, s[8:9]
	global_load_dword v124, v130, s[8:9]
	global_load_dwordx2 v[140:141], v130, s[8:9]
	global_load_dwordx2 v[142:143], v130, s[8:9] offset:1024
	global_load_dword v144, v131, s[8:9]
	global_load_dword v145, v132, s[8:9]
	global_load_dword v146, v133, s[8:9]
	global_load_dword v147, v134, s[8:9]
	s_add_u32 s8, s8, 0x34000
	s_addc_u32 s9, s9, 0
	global_load_dword v124, v130, s[8:9]
	global_load_dword v124, v130, s[8:9]
	global_load_dwordx2 v[100:101], v130, s[8:9]
	global_load_dwordx2 v[102:103], v130, s[8:9] offset:1024
	global_load_dword v104, v131, s[8:9]
	global_load_dword v105, v132, s[8:9]
	global_load_dword v106, v133, s[8:9]
	global_load_dword v107, v134, s[8:9]
	s_add_u32 s8, s8, 0x34000
	s_addc_u32 s9, s9, 0
	s_waitcnt lgkmcnt(0)
	s_barrier
	.p2align 6
.Lgla_loop_hgrn:
	ds_read2_b32 v[180:181], v149 offset0:0 offset1:32
	ds_read2_b32 v[182:183], v149 offset0:64 offset1:96
	ds_read2_b32 v[184:185], v149 offset0:128 offset1:160
	ds_read2_b32 v[186:187], v149 offset0:192 offset1:224
	v_mfma_f32_16x16x4_f32 v[0:3], v40, v52, v[0:3]
	s_waitcnt lgkmcnt(0)
	v_add_f32_e32 v188, v180, v181
	v_add_f32_e32 v188, v188, v182
	v_mfma_f32_16x16x4_f32 v[4:7], v40, v53, v[4:7]
	v_add_f32_e32 v188, v188, v183
	v_add_f32_e32 v188, v188, v184
	v_add_f32_e32 v188, v188, v185
	v_mfma_f32_16x16x4_f32 v[0:3], v41, v54, v[0:3]
	v_add_f32_e32 v188, v188, v186
	v_add_f32_e32 v188, v188, v187
	v_mul_f32_e32 v189, v188, v188
	v_mfma_f32_16x16x4_f32 v[4:7], v41, v55, v[4:7]
	v_cvt_pk_bf16_f32 v192, v188, v129
	v_mov_b32_e32 v193, v188
	v_mov_b32_e32 v194, v189
	v_mfma_f32_16x16x4_f32 v[0:3], v42, v56, v[0:3]
	global_store_short v135, v192, s[10:11]
	s_nop 1
	v_permlane16_swap_b32_e32 v188, v193
	v_permlane16_swap_b32_e32 v189, v194
	v_mfma_f32_16x16x4_f32 v[4:7], v42, v57, v[4:7]
	v_add_f32_e32 v188, v188, v193
	v_add_f32_e32 v189, v189, v194
	s_nop 1
	v_add_f32_dpp v188, v188, v188 row_ror:8 row_mask:0xf bank_mask:0xf
	v_mfma_f32_16x16x4_f32 v[0:3], v43, v58, v[0:3]
	v_add_f32_dpp v189, v189, v189 row_ror:8 row_mask:0xf bank_mask:0xf
	s_nop 1
	v_add_f32_dpp v188, v188, v188 row_ror:4 row_mask:0xf bank_mask:0xf
	v_add_f32_dpp v189, v189, v189 row_ror:4 row_mask:0xf bank_mask:0xf
	v_mfma_f32_16x16x4_f32 v[4:7], v43, v59, v[4:7]
	s_nop 1
	v_add_f32_dpp v188, v188, v188 row_ror:2 row_mask:0xf bank_mask:0xf
	v_add_f32_dpp v189, v189, v189 row_ror:2 row_mask:0xf bank_mask:0xf
	s_nop 1
	v_add_f32_dpp v188, v188, v188 row_ror:1 row_mask:0xf bank_mask:0xf
	s_nop 7
	v_pk_mul_f32 v[0:1], v[0:1], v[60:61]
	v_pk_mul_f32 v[2:3], v[2:3], v[62:63]
	v_pk_mul_f32 v[4:5], v[4:5], v[60:61]
	v_pk_mul_f32 v[6:7], v[6:7], v[62:63]
	s_nop 1
	v_mfma_f32_16x16x4_f32 v[16:19], v24, v20, 0
	s_waitcnt vmcnt(25)
	v_lshlrev_b32_e32 v28, 16, v108
	v_and_b32_e32 v29, s69, v108
	v_add_f32_dpp v189, v189, v189 row_ror:1 row_mask:0xf bank_mask:0xf
	v_mfma_f32_16x16x4_f32 v[8:11], v0, v20, 0
	v_lshlrev_b32_e32 v30, 16, v109
	v_and_b32_e32 v31, s69, v109
	v_lshlrev_b32_e32 v32, 16, v110
	v_mov_b32_e32 v190, 0
	v_mfma_f32_16x16x4_f32 v[16:19], v25, v21, v[16:19]
	v_and_b32_e32 v33, s69, v110
	v_lshlrev_b32_e32 v34, 16, v111
	v_and_b32_e32 v35, s69, v111
	v_mov_b32_e32 v191, 0
	v_mfma_f32_16x16x4_f32 v[12:15], v4, v20, 0
	v_lshlrev_b32_e32 v52, 16, v112
	v_and_b32_e32 v53, s69, v112
	v_lshlrev_b32_e32 v54, 16, v113
	s_nop 0
	s_mov_b64 exec, s[18:19]
	global_store_dwordx4 v139, v[188:191], s[12:13]
	s_mov_b64 exec, -1
	s_cmp_eq_u32 s15, 512
	s_cselect_b32 s20, 0, 0x10000
	s_cselect_b32 s21, 0, 0x1000
	s_add_u32 s10, s10, s20
	s_addc_u32 s11, s11, 0
	s_add_u32 s12, s12, s21
	s_addc_u32 s13, s13, 0
	v_mfma_f32_16x16x4_f32 v[16:19], v26, v22, v[16:19]
	v_and_b32_e32 v55, s69, v113
	v_lshlrev_b32_e32 v56, 16, v114
	v_and_b32_e32 v57, s69, v114
	v_mfma_f32_16x16x4_f32 v[8:11], v1, v21, v[8:11]
	v_lshlrev_b32_e32 v58, 16, v115
	v_and_b32_e32 v59, s69, v115
	global_load_dwordx2 v[108:109], v130, s[8:9]
	global_load_dwordx2 v[110:111], v130, s[8:9] offset:1024
	global_load_dword v112, v131, s[8:9]
	global_load_dword v113, v132, s[8:9]
	global_load_dword v114, v133, s[8:9]
	global_load_dword v115, v134, s[8:9]
	s_add_u32 s8, s8, 0x34000
	s_addc_u32 s9, s9, 0
	v_mfma_f32_16x16x4_f32 v[16:19], v27, v23, v[16:19]
	v_mul_f32_e32 v32, 0x3fb8aa3b, v32
	v_mul_f32_e32 v33, 0x3fb8aa3b, v33
	v_mul_f32_e32 v34, 0x3fb8aa3b, v34
	v_mfma_f32_16x16x4_f32 v[12:15], v5, v21, v[12:15]
	v_mul_f32_e32 v35, 0x3fb8aa3b, v35
	v_add_f32_dpp v80, v32, v32 row_shl:1 row_mask:0xf bank_mask:0xf bound_ctrl:0
	v_add_f32_dpp v81, v33, v33 row_shl:1 row_mask:0xf bank_mask:0xf bound_ctrl:0
	v_mfma_f32_16x16x4_f32 v[8:11], v2, v22, v[8:11]
	v_add_f32_dpp v82, v34, v34 row_shl:1 row_mask:0xf bank_mask:0xf bound_ctrl:0
	v_add_f32_dpp v83, v35, v35 row_shl:1 row_mask:0xf bank_mask:0xf bound_ctrl:0
	v_add_f32_dpp v80, v80, v80 row_shl:2 row_mask:0xf bank_mask:0xf bound_ctrl:0
	v_mfma_f32_16x16x4_f32 v[12:15], v6, v22, v[12:15]
	v_add_f32_dpp v81, v81, v81 row_shl:2 row_mask:0xf bank_mask:0xf bound_ctrl:0
	v_add_f32_dpp v82, v82, v82 row_shl:2 row_mask:0xf bank_mask:0xf bound_ctrl:0
	v_add_f32_dpp v83, v83, v83 row_shl:2 row_mask:0xf bank_mask:0xf bound_ctrl:0
	v_mfma_f32_16x16x4_f32 v[8:11], v3, v23, v[8:11]
	v_add_f32_dpp v80, v80, v80 row_shl:4 row_mask:0xf bank_mask:0xf bound_ctrl:0
	v_add_f32_dpp v81, v81, v81 row_shl:4 row_mask:0xf bank_mask:0xf bound_ctrl:0
	v_add_f32_dpp v82, v82, v82 row_shl:4 row_mask:0xf bank_mask:0xf bound_ctrl:0
	v_mfma_f32_16x16x4_f32 v[12:15], v7, v23, v[12:15]
	v_add_f32_dpp v83, v83, v83 row_shl:4 row_mask:0xf bank_mask:0xf bound_ctrl:0
	v_add_f32_dpp v80, v80, v80 row_shl:8 row_mask:0xf bank_mask:0xf bound_ctrl:0
	v_add_f32_dpp v81, v81, v81 row_shl:8 row_mask:0xf bank_mask:0xf bound_ctrl:0
	v_pk_mul_f32 v[16:17], v[16:17], v[74:75]
	v_pk_mul_f32 v[18:19], v[18:19], v[76:77]
	s_nop 1
	v_permlane16_swap_b32_e32 v16, v17
	v_permlane16_swap_b32_e32 v18, v19
	s_nop 1
	v_permlane32_swap_b32_e32 v16, v18
	v_permlane32_swap_b32_e32 v17, v19
	s_nop 1
	v_mfma_f32_16x16x4_f32 v[8:11], v44, v16, v[8:11]
	v_add_f32_dpp v82, v82, v82 row_shl:8 row_mask:0xf bank_mask:0xf bound_ctrl:0
	v_add_f32_dpp v83, v83, v83 row_shl:8 row_mask:0xf bank_mask:0xf bound_ctrl:0
	v_exp_f32_e32 v84, v32
	v_exp_f32_e32 v85, v33
	v_exp_f32_e32 v86, v34
	v_mfma_f32_16x16x4_f32 v[12:15], v45, v16, v[12:15]
	v_exp_f32_e32 v87, v35
	ds_swizzle_b32 v96, v80 offset:swizzle(BITMASK_PERM,"p0000")
	ds_swizzle_b32 v97, v81 offset:swizzle(BITMASK_PERM,"p0000")
	ds_swizzle_b32 v98, v82 offset:swizzle(BITMASK_PERM,"p0000")
	ds_swizzle_b32 v99, v83 offset:swizzle(BITMASK_PERM,"p0000")
	v_mfma_f32_16x16x4_f32 v[8:11], v46, v17, v[8:11]
	v_sub_f32_e32 v88, v80, v32
	v_sub_f32_e32 v89, v81, v33
	v_sub_f32_e32 v90, v82, v34
	v_sub_f32_e32 v91, v83, v35
	v_max_f32_e32 v88, 0xc2fc0000, v88
	v_mfma_f32_16x16x4_f32 v[12:15], v47, v17, v[12:15]
	v_max_f32_e32 v89, 0xc2fc0000, v89
	v_max_f32_e32 v90, 0xc2fc0000, v90
	v_max_f32_e32 v91, 0xc2fc0000, v91
	v_sub_f32_e32 v84, 1.0, v84
	v_sub_f32_e32 v85, 1.0, v85
	v_mfma_f32_16x16x4_f32 v[8:11], v48, v18, v[8:11]
	v_sub_f32_e32 v86, 1.0, v86
	v_sub_f32_e32 v87, 1.0, v87
	v_exp_f32_e64 v92, -v88
	v_exp_f32_e64 v93, -v89
	v_exp_f32_e64 v94, -v90
	v_mfma_f32_16x16x4_f32 v[12:15], v49, v18, v[12:15]
	v_exp_f32_e64 v95, -v91
	v_exp_f32_e32 v88, v88
	v_exp_f32_e32 v89, v89
	v_exp_f32_e32 v90, v90
	v_exp_f32_e32 v91, v91
	v_mfma_f32_16x16x4_f32 v[8:11], v50, v19, v[8:11]
	s_waitcnt lgkmcnt(0)
	v_exp_f32_e32 v64, v96
	v_exp_f32_e32 v65, v97
	v_exp_f32_e32 v66, v98
	v_exp_f32_e32 v67, v99
	v_mfma_f32_16x16x4_f32 v[12:15], v51, v19, v[12:15]
	v_mul_f32_e32 v32, v84, v88
	v_mul_f32_e32 v33, v85, v89
	v_mul_f32_e32 v34, v86, v90
	v_mul_f32_e32 v35, v87, v91
	v_mul_f32_e32 v28, v28, v92
	v_mul_f32_e32 v29, v29, v93
	v_mul_f32_e32 v30, v30, v94
	v_mul_f32_e32 v31, v31, v95
	ds_write_b128 v153, v[32:35]
	ds_read_b32 v40, v154 offset:0
	ds_read_b32 v41, v154 offset:320
	ds_read_b32 v42, v154 offset:640
	ds_read_b32 v43, v154 offset:960
	s_waitcnt lgkmcnt(0)
	s_nop 7
	s_nop 1
	ds_write2_b32 v150, v8, v12 offset0:0 offset1:1
	ds_write2_b32 v150, v9, v13 offset0:2 offset1:3
	ds_write2_b32 v150, v10, v14 offset0:4 offset1:5
	ds_write2_b32 v150, v11, v15 offset0:6 offset1:7
	s_sub_u32 s15, s15, 1
	s_waitcnt lgkmcnt(0)
	s_barrier
	ds_read2_b32 v[180:181], v148 offset0:0 offset1:32
	ds_read2_b32 v[182:183], v148 offset0:64 offset1:96
	ds_read2_b32 v[184:185], v148 offset0:128 offset1:160
	ds_read2_b32 v[186:187], v148 offset0:192 offset1:224
	v_mfma_f32_16x16x4_f32 v[0:3], v36, v44, v[0:3]
	s_waitcnt lgkmcnt(0)
	v_add_f32_e32 v188, v180, v181
	v_add_f32_e32 v188, v188, v182
	v_mfma_f32_16x16x4_f32 v[4:7], v36, v45, v[4:7]
	v_add_f32_e32 v188, v188, v183
	v_add_f32_e32 v188, v188, v184
	v_add_f32_e32 v188, v188, v185
	v_mfma_f32_16x16x4_f32 v[0:3], v37, v46, v[0:3]
	v_add_f32_e32 v188, v188, v186
	v_add_f32_e32 v188, v188, v187
	v_mul_f32_e32 v189, v188, v188
	v_mfma_f32_16x16x4_f32 v[4:7], v37, v47, v[4:7]
	v_cvt_pk_bf16_f32 v192, v188, v129
	v_mov_b32_e32 v193, v188
	v_mov_b32_e32 v194, v189
	v_mfma_f32_16x16x4_f32 v[0:3], v38, v48, v[0:3]
	global_store_short v135, v192, s[10:11]
	s_nop 1
	v_permlane16_swap_b32_e32 v188, v193
	v_permlane16_swap_b32_e32 v189, v194
	v_mfma_f32_16x16x4_f32 v[4:7], v38, v49, v[4:7]
	v_add_f32_e32 v188, v188, v193
	v_add_f32_e32 v189, v189, v194
	s_nop 1
	v_add_f32_dpp v188, v188, v188 row_ror:8 row_mask:0xf bank_mask:0xf
	v_mfma_f32_16x16x4_f32 v[0:3], v39, v50, v[0:3]
	v_add_f32_dpp v189, v189, v189 row_ror:8 row_mask:0xf bank_mask:0xf
	s_nop 1
	v_add_f32_dpp v188, v188, v188 row_ror:4 row_mask:0xf bank_mask:0xf
	v_add_f32_dpp v189, v189, v189 row_ror:4 row_mask:0xf bank_mask:0xf
	v_mfma_f32_16x16x4_f32 v[4:7], v39, v51, v[4:7]
	s_nop 1
	v_add_f32_dpp v188, v188, v188 row_ror:2 row_mask:0xf bank_mask:0xf
	v_add_f32_dpp v189, v189, v189 row_ror:2 row_mask:0xf bank_mask:0xf
	s_nop 1
	v_add_f32_dpp v188, v188, v188 row_ror:1 row_mask:0xf bank_mask:0xf
	s_nop 7
	v_pk_mul_f32 v[0:1], v[0:1], v[64:65]
	v_pk_mul_f32 v[2:3], v[2:3], v[66:67]
	v_pk_mul_f32 v[4:5], v[4:5], v[64:65]
	v_pk_mul_f32 v[6:7], v[6:7], v[66:67]
	s_nop 1
	v_mfma_f32_16x16x4_f32 v[16:19], v32, v28, 0
	s_waitcnt vmcnt(25)
	v_lshlrev_b32_e32 v20, 16, v116
	v_and_b32_e32 v21, s69, v116
	v_add_f32_dpp v189, v189, v189 row_ror:1 row_mask:0xf bank_mask:0xf
	v_mfma_f32_16x16x4_f32 v[8:11], v0, v28, 0
	v_lshlrev_b32_e32 v22, 16, v117
	v_and_b32_e32 v23, s69, v117
	v_lshlrev_b32_e32 v24, 16, v118
	v_mov_b32_e32 v190, 0
	v_mfma_f32_16x16x4_f32 v[16:19], v33, v29, v[16:19]
	v_and_b32_e32 v25, s69, v118
	v_lshlrev_b32_e32 v26, 16, v119
	v_and_b32_e32 v27, s69, v119
	v_mov_b32_e32 v191, 0
	v_mfma_f32_16x16x4_f32 v[12:15], v4, v28, 0
	v_lshlrev_b32_e32 v44, 16, v120
	v_and_b32_e32 v45, s69, v120
	v_lshlrev_b32_e32 v46, 16, v121
	s_nop 0
	s_mov_b64 exec, s[18:19]
	global_store_dwordx4 v139, v[188:191], s[12:13]
	s_mov_b64 exec, -1
	s_cmp_eq_u32 s15, 512
	s_cselect_b32 s20, 0, 0x10000
	s_cselect_b32 s21, 0, 0x1000
	s_add_u32 s10, s10, s20
	s_addc_u32 s11, s11, 0
	s_add_u32 s12, s12, s21
	s_addc_u32 s13, s13, 0
	v_mfma_f32_16x16x4_f32 v[16:19], v34, v30, v[16:19]
	v_and_b32_e32 v47, s69, v121
	v_lshlrev_b32_e32 v48, 16, v122
	v_and_b32_e32 v49, s69, v122
	v_mfma_f32_16x16x4_f32 v[8:11], v1, v29, v[8:11]
	v_lshlrev_b32_e32 v50, 16, v123
	v_and_b32_e32 v51, s69, v123
	global_load_dwordx2 v[116:117], v130, s[8:9]
	global_load_dwordx2 v[118:119], v130, s[8:9] offset:1024
	global_load_dword v120, v131, s[8:9]
	global_load_dword v121, v132, s[8:9]
	global_load_dword v122, v133, s[8:9]
	global_load_dword v123, v134, s[8:9]
	s_add_u32 s8, s8, 0x34000
	s_addc_u32 s9, s9, 0
	v_mfma_f32_16x16x4_f32 v[16:19], v35, v31, v[16:19]
	v_mul_f32_e32 v24, 0x3fb8aa3b, v24
	v_mul_f32_e32 v25, 0x3fb8aa3b, v25
	v_mul_f32_e32 v26, 0x3fb8aa3b, v26
	v_mfma_f32_16x16x4_f32 v[12:15], v5, v29, v[12:15]
	v_mul_f32_e32 v27, 0x3fb8aa3b, v27
	v_add_f32_dpp v80, v24, v24 row_shl:1 row_mask:0xf bank_mask:0xf bound_ctrl:0
	v_add_f32_dpp v81, v25, v25 row_shl:1 row_mask:0xf bank_mask:0xf bound_ctrl:0
	v_mfma_f32_16x16x4_f32 v[8:11], v2, v30, v[8:11]
	v_add_f32_dpp v82, v26, v26 row_shl:1 row_mask:0xf bank_mask:0xf bound_ctrl:0
	v_add_f32_dpp v83, v27, v27 row_shl:1 row_mask:0xf bank_mask:0xf bound_ctrl:0
	v_add_f32_dpp v80, v80, v80 row_shl:2 row_mask:0xf bank_mask:0xf bound_ctrl:0
	v_mfma_f32_16x16x4_f32 v[12:15], v6, v30, v[12:15]
	v_add_f32_dpp v81, v81, v81 row_shl:2 row_mask:0xf bank_mask:0xf bound_ctrl:0
	v_add_f32_dpp v82, v82, v82 row_shl:2 row_mask:0xf bank_mask:0xf bound_ctrl:0
	v_add_f32_dpp v83, v83, v83 row_shl:2 row_mask:0xf bank_mask:0xf bound_ctrl:0
	v_mfma_f32_16x16x4_f32 v[8:11], v3, v31, v[8:11]
	v_add_f32_dpp v80, v80, v80 row_shl:4 row_mask:0xf bank_mask:0xf bound_ctrl:0
	v_add_f32_dpp v81, v81, v81 row_shl:4 row_mask:0xf bank_mask:0xf bound_ctrl:0
	v_add_f32_dpp v82, v82, v82 row_shl:4 row_mask:0xf bank_mask:0xf bound_ctrl:0
	v_mfma_f32_16x16x4_f32 v[12:15], v7, v31, v[12:15]
	v_add_f32_dpp v83, v83, v83 row_shl:4 row_mask:0xf bank_mask:0xf bound_ctrl:0
	v_add_f32_dpp v80, v80, v80 row_shl:8 row_mask:0xf bank_mask:0xf bound_ctrl:0
	v_add_f32_dpp v81, v81, v81 row_shl:8 row_mask:0xf bank_mask:0xf bound_ctrl:0
	v_pk_mul_f32 v[16:17], v[16:17], v[74:75]
	v_pk_mul_f32 v[18:19], v[18:19], v[76:77]
	s_nop 1
	v_permlane16_swap_b32_e32 v16, v17
	v_permlane16_swap_b32_e32 v18, v19
	s_nop 1
	v_permlane32_swap_b32_e32 v16, v18
	v_permlane32_swap_b32_e32 v17, v19
	s_nop 1
	v_mfma_f32_16x16x4_f32 v[8:11], v52, v16, v[8:11]
	v_add_f32_dpp v82, v82, v82 row_shl:8 row_mask:0xf bank_mask:0xf bound_ctrl:0
	v_add_f32_dpp v83, v83, v83 row_shl:8 row_mask:0xf bank_mask:0xf bound_ctrl:0
	v_exp_f32_e32 v84, v24
	v_exp_f32_e32 v85, v25
	v_exp_f32_e32 v86, v26
	v_mfma_f32_16x16x4_f32 v[12:15], v53, v16, v[12:15]
	v_exp_f32_e32 v87, v27
	ds_swizzle_b32 v96, v80 offset:swizzle(BITMASK_PERM,"p0000")
	ds_swizzle_b32 v97, v81 offset:swizzle(BITMASK_PERM,"p0000")
	ds_swizzle_b32 v98, v82 offset:swizzle(BITMASK_PERM,"p0000")
	ds_swizzle_b32 v99, v83 offset:swizzle(BITMASK_PERM,"p0000")
	v_mfma_f32_16x16x4_f32 v[8:11], v54, v17, v[8:11]
	v_sub_f32_e32 v88, v80, v24
	v_sub_f32_e32 v89, v81, v25
	v_sub_f32_e32 v90, v82, v26
	v_sub_f32_e32 v91, v83, v27
	v_max_f32_e32 v88, 0xc2fc0000, v88
	v_mfma_f32_16x16x4_f32 v[12:15], v55, v17, v[12:15]
	v_max_f32_e32 v89, 0xc2fc0000, v89
	v_max_f32_e32 v90, 0xc2fc0000, v90
	v_max_f32_e32 v91, 0xc2fc0000, v91
	v_sub_f32_e32 v84, 1.0, v84
	v_sub_f32_e32 v85, 1.0, v85
	v_mfma_f32_16x16x4_f32 v[8:11], v56, v18, v[8:11]
	v_sub_f32_e32 v86, 1.0, v86
	v_sub_f32_e32 v87, 1.0, v87
	v_exp_f32_e64 v92, -v88
	v_exp_f32_e64 v93, -v89
	v_exp_f32_e64 v94, -v90
	v_mfma_f32_16x16x4_f32 v[12:15], v57, v18, v[12:15]
	v_exp_f32_e64 v95, -v91
	v_exp_f32_e32 v88, v88
	v_exp_f32_e32 v89, v89
	v_exp_f32_e32 v90, v90
	v_exp_f32_e32 v91, v91
	v_mfma_f32_16x16x4_f32 v[8:11], v58, v19, v[8:11]
	s_waitcnt lgkmcnt(0)
	v_exp_f32_e32 v60, v96
	v_exp_f32_e32 v61, v97
	v_exp_f32_e32 v62, v98
	v_exp_f32_e32 v63, v99
	v_mfma_f32_16x16x4_f32 v[12:15], v59, v19, v[12:15]
	v_mul_f32_e32 v24, v84, v88
	v_mul_f32_e32 v25, v85, v89
	v_mul_f32_e32 v26, v86, v90
	v_mul_f32_e32 v27, v87, v91
	v_mul_f32_e32 v20, v20, v92
	v_mul_f32_e32 v21, v21, v93
	v_mul_f32_e32 v22, v22, v94
	v_mul_f32_e32 v23, v23, v95
	ds_write_b128 v153, v[24:27]
	ds_read_b32 v36, v154 offset:0
	ds_read_b32 v37, v154 offset:320
	ds_read_b32 v38, v154 offset:640
	ds_read_b32 v39, v154 offset:960
	s_waitcnt lgkmcnt(0)
	s_nop 7
	s_nop 1
	ds_write2_b32 v152, v8, v12 offset0:0 offset1:1
	ds_write2_b32 v152, v9, v13 offset0:2 offset1:3
	ds_write2_b32 v152, v10, v14 offset0:4 offset1:5
	ds_write2_b32 v152, v11, v15 offset0:6 offset1:7
	s_sub_u32 s15, s15, 1
	s_waitcnt lgkmcnt(0)
	s_barrier
	ds_read2_b32 v[180:181], v149 offset0:0 offset1:32
	ds_read2_b32 v[182:183], v149 offset0:64 offset1:96
	ds_read2_b32 v[184:185], v149 offset0:128 offset1:160
	ds_read2_b32 v[186:187], v149 offset0:192 offset1:224
	v_mfma_f32_16x16x4_f32 v[0:3], v40, v52, v[0:3]
	s_waitcnt lgkmcnt(0)
	v_add_f32_e32 v188, v180, v181
	v_add_f32_e32 v188, v188, v182
	v_mfma_f32_16x16x4_f32 v[4:7], v40, v53, v[4:7]
	v_add_f32_e32 v188, v188, v183
	v_add_f32_e32 v188, v188, v184
	v_add_f32_e32 v188, v188, v185
	v_mfma_f32_16x16x4_f32 v[0:3], v41, v54, v[0:3]
	v_add_f32_e32 v188, v188, v186
	v_add_f32_e32 v188, v188, v187
	v_mul_f32_e32 v189, v188, v188
	v_mfma_f32_16x16x4_f32 v[4:7], v41, v55, v[4:7]
	v_cvt_pk_bf16_f32 v192, v188, v129
	v_mov_b32_e32 v193, v188
	v_mov_b32_e32 v194, v189
	v_mfma_f32_16x16x4_f32 v[0:3], v42, v56, v[0:3]
	global_store_short v135, v192, s[10:11]
	s_nop 1
	v_permlane16_swap_b32_e32 v188, v193
	v_permlane16_swap_b32_e32 v189, v194
	v_mfma_f32_16x16x4_f32 v[4:7], v42, v57, v[4:7]
	v_add_f32_e32 v188, v188, v193
	v_add_f32_e32 v189, v189, v194
	s_nop 1
	v_add_f32_dpp v188, v188, v188 row_ror:8 row_mask:0xf bank_mask:0xf
	v_mfma_f32_16x16x4_f32 v[0:3], v43, v58, v[0:3]
	v_add_f32_dpp v189, v189, v189 row_ror:8 row_mask:0xf bank_mask:0xf
	s_nop 1
	v_add_f32_dpp v188, v188, v188 row_ror:4 row_mask:0xf bank_mask:0xf
	v_add_f32_dpp v189, v189, v189 row_ror:4 row_mask:0xf bank_mask:0xf
	v_mfma_f32_16x16x4_f32 v[4:7], v43, v59, v[4:7]
	s_nop 1
	v_add_f32_dpp v188, v188, v188 row_ror:2 row_mask:0xf bank_mask:0xf
	v_add_f32_dpp v189, v189, v189 row_ror:2 row_mask:0xf bank_mask:0xf
	s_nop 1
	v_add_f32_dpp v188, v188, v188 row_ror:1 row_mask:0xf bank_mask:0xf
	s_nop 7
	v_pk_mul_f32 v[0:1], v[0:1], v[60:61]
	v_pk_mul_f32 v[2:3], v[2:3], v[62:63]
	v_pk_mul_f32 v[4:5], v[4:5], v[60:61]
	v_pk_mul_f32 v[6:7], v[6:7], v[62:63]
	s_nop 1
	v_mfma_f32_16x16x4_f32 v[16:19], v24, v20, 0
	s_waitcnt vmcnt(25)
	v_lshlrev_b32_e32 v28, 16, v140
	v_and_b32_e32 v29, s69, v140
	v_add_f32_dpp v189, v189, v189 row_ror:1 row_mask:0xf bank_mask:0xf
	v_mfma_f32_16x16x4_f32 v[8:11], v0, v20, 0
	v_lshlrev_b32_e32 v30, 16, v141
	v_and_b32_e32 v31, s69, v141
	v_lshlrev_b32_e32 v32, 16, v142
	v_mov_b32_e32 v190, 0
	v_mfma_f32_16x16x4_f32 v[16:19], v25, v21, v[16:19]
	v_and_b32_e32 v33, s69, v142
	v_lshlrev_b32_e32 v34, 16, v143
	v_and_b32_e32 v35, s69, v143
	v_mov_b32_e32 v191, 0
	v_mfma_f32_16x16x4_f32 v[12:15], v4, v20, 0
	v_lshlrev_b32_e32 v52, 16, v144
	v_and_b32_e32 v53, s69, v144
	v_lshlrev_b32_e32 v54, 16, v145
	s_nop 0
	s_mov_b64 exec, s[18:19]
	global_store_dwordx4 v139, v[188:191], s[12:13]
	s_mov_b64 exec, -1
	s_cmp_eq_u32 s15, 512
	s_cselect_b32 s20, 0, 0x10000
	s_cselect_b32 s21, 0, 0x1000
	s_add_u32 s10, s10, s20
	s_addc_u32 s11, s11, 0
	s_add_u32 s12, s12, s21
	s_addc_u32 s13, s13, 0
	v_mfma_f32_16x16x4_f32 v[16:19], v26, v22, v[16:19]
	v_and_b32_e32 v55, s69, v145
	v_lshlrev_b32_e32 v56, 16, v146
	v_and_b32_e32 v57, s69, v146
	v_mfma_f32_16x16x4_f32 v[8:11], v1, v21, v[8:11]
	v_lshlrev_b32_e32 v58, 16, v147
	v_and_b32_e32 v59, s69, v147
	global_load_dwordx2 v[140:141], v130, s[8:9]
	global_load_dwordx2 v[142:143], v130, s[8:9] offset:1024
	global_load_dword v144, v131, s[8:9]
	global_load_dword v145, v132, s[8:9]
	global_load_dword v146, v133, s[8:9]
	global_load_dword v147, v134, s[8:9]
	s_add_u32 s8, s8, 0x34000
	s_addc_u32 s9, s9, 0
	v_mfma_f32_16x16x4_f32 v[16:19], v27, v23, v[16:19]
	v_mul_f32_e32 v32, 0x3fb8aa3b, v32
	v_mul_f32_e32 v33, 0x3fb8aa3b, v33
	v_mul_f32_e32 v34, 0x3fb8aa3b, v34
	v_mfma_f32_16x16x4_f32 v[12:15], v5, v21, v[12:15]
	v_mul_f32_e32 v35, 0x3fb8aa3b, v35
	v_add_f32_dpp v80, v32, v32 row_shl:1 row_mask:0xf bank_mask:0xf bound_ctrl:0
	v_add_f32_dpp v81, v33, v33 row_shl:1 row_mask:0xf bank_mask:0xf bound_ctrl:0
	v_mfma_f32_16x16x4_f32 v[8:11], v2, v22, v[8:11]
	v_add_f32_dpp v82, v34, v34 row_shl:1 row_mask:0xf bank_mask:0xf bound_ctrl:0
	v_add_f32_dpp v83, v35, v35 row_shl:1 row_mask:0xf bank_mask:0xf bound_ctrl:0
	v_add_f32_dpp v80, v80, v80 row_shl:2 row_mask:0xf bank_mask:0xf bound_ctrl:0
	v_mfma_f32_16x16x4_f32 v[12:15], v6, v22, v[12:15]
	v_add_f32_dpp v81, v81, v81 row_shl:2 row_mask:0xf bank_mask:0xf bound_ctrl:0
	v_add_f32_dpp v82, v82, v82 row_shl:2 row_mask:0xf bank_mask:0xf bound_ctrl:0
	v_add_f32_dpp v83, v83, v83 row_shl:2 row_mask:0xf bank_mask:0xf bound_ctrl:0
	v_mfma_f32_16x16x4_f32 v[8:11], v3, v23, v[8:11]
	v_add_f32_dpp v80, v80, v80 row_shl:4 row_mask:0xf bank_mask:0xf bound_ctrl:0
	v_add_f32_dpp v81, v81, v81 row_shl:4 row_mask:0xf bank_mask:0xf bound_ctrl:0
	v_add_f32_dpp v82, v82, v82 row_shl:4 row_mask:0xf bank_mask:0xf bound_ctrl:0
	v_mfma_f32_16x16x4_f32 v[12:15], v7, v23, v[12:15]
	v_add_f32_dpp v83, v83, v83 row_shl:4 row_mask:0xf bank_mask:0xf bound_ctrl:0
	v_add_f32_dpp v80, v80, v80 row_shl:8 row_mask:0xf bank_mask:0xf bound_ctrl:0
	v_add_f32_dpp v81, v81, v81 row_shl:8 row_mask:0xf bank_mask:0xf bound_ctrl:0
	v_pk_mul_f32 v[16:17], v[16:17], v[74:75]
	v_pk_mul_f32 v[18:19], v[18:19], v[76:77]
	s_nop 1
	v_permlane16_swap_b32_e32 v16, v17
	v_permlane16_swap_b32_e32 v18, v19
	s_nop 1
	v_permlane32_swap_b32_e32 v16, v18
	v_permlane32_swap_b32_e32 v17, v19
	s_nop 1
	v_mfma_f32_16x16x4_f32 v[8:11], v44, v16, v[8:11]
	v_add_f32_dpp v82, v82, v82 row_shl:8 row_mask:0xf bank_mask:0xf bound_ctrl:0
	v_add_f32_dpp v83, v83, v83 row_shl:8 row_mask:0xf bank_mask:0xf bound_ctrl:0
	v_exp_f32_e32 v84, v32
	v_exp_f32_e32 v85, v33
	v_exp_f32_e32 v86, v34
	v_mfma_f32_16x16x4_f32 v[12:15], v45, v16, v[12:15]
	v_exp_f32_e32 v87, v35
	ds_swizzle_b32 v96, v80 offset:swizzle(BITMASK_PERM,"p0000")
	ds_swizzle_b32 v97, v81 offset:swizzle(BITMASK_PERM,"p0000")
	ds_swizzle_b32 v98, v82 offset:swizzle(BITMASK_PERM,"p0000")
	ds_swizzle_b32 v99, v83 offset:swizzle(BITMASK_PERM,"p0000")
	v_mfma_f32_16x16x4_f32 v[8:11], v46, v17, v[8:11]
	v_sub_f32_e32 v88, v80, v32
	v_sub_f32_e32 v89, v81, v33
	v_sub_f32_e32 v90, v82, v34
	v_sub_f32_e32 v91, v83, v35
	v_max_f32_e32 v88, 0xc2fc0000, v88
	v_mfma_f32_16x16x4_f32 v[12:15], v47, v17, v[12:15]
	v_max_f32_e32 v89, 0xc2fc0000, v89
	v_max_f32_e32 v90, 0xc2fc0000, v90
	v_max_f32_e32 v91, 0xc2fc0000, v91
	v_sub_f32_e32 v84, 1.0, v84
	v_sub_f32_e32 v85, 1.0, v85
	v_mfma_f32_16x16x4_f32 v[8:11], v48, v18, v[8:11]
	v_sub_f32_e32 v86, 1.0, v86
	v_sub_f32_e32 v87, 1.0, v87
	v_exp_f32_e64 v92, -v88
	v_exp_f32_e64 v93, -v89
	v_exp_f32_e64 v94, -v90
	v_mfma_f32_16x16x4_f32 v[12:15], v49, v18, v[12:15]
	v_exp_f32_e64 v95, -v91
	v_exp_f32_e32 v88, v88
	v_exp_f32_e32 v89, v89
	v_exp_f32_e32 v90, v90
	v_exp_f32_e32 v91, v91
	v_mfma_f32_16x16x4_f32 v[8:11], v50, v19, v[8:11]
	s_waitcnt lgkmcnt(0)
	v_exp_f32_e32 v64, v96
	v_exp_f32_e32 v65, v97
	v_exp_f32_e32 v66, v98
	v_exp_f32_e32 v67, v99
	v_mfma_f32_16x16x4_f32 v[12:15], v51, v19, v[12:15]
	v_mul_f32_e32 v32, v84, v88
	v_mul_f32_e32 v33, v85, v89
	v_mul_f32_e32 v34, v86, v90
	v_mul_f32_e32 v35, v87, v91
	v_mul_f32_e32 v28, v28, v92
	v_mul_f32_e32 v29, v29, v93
	v_mul_f32_e32 v30, v30, v94
	v_mul_f32_e32 v31, v31, v95
	ds_write_b128 v153, v[32:35]
	ds_read_b32 v40, v154 offset:0
	ds_read_b32 v41, v154 offset:320
	ds_read_b32 v42, v154 offset:640
	ds_read_b32 v43, v154 offset:960
	s_waitcnt lgkmcnt(0)
	s_nop 7
	s_nop 1
	ds_write2_b32 v150, v8, v12 offset0:0 offset1:1
	ds_write2_b32 v150, v9, v13 offset0:2 offset1:3
	ds_write2_b32 v150, v10, v14 offset0:4 offset1:5
	ds_write2_b32 v150, v11, v15 offset0:6 offset1:7
	s_sub_u32 s15, s15, 1
	s_waitcnt lgkmcnt(0)
	s_barrier
	ds_read2_b32 v[180:181], v148 offset0:0 offset1:32
	ds_read2_b32 v[182:183], v148 offset0:64 offset1:96
	ds_read2_b32 v[184:185], v148 offset0:128 offset1:160
	ds_read2_b32 v[186:187], v148 offset0:192 offset1:224
	v_mfma_f32_16x16x4_f32 v[0:3], v36, v44, v[0:3]
	s_waitcnt lgkmcnt(0)
	v_add_f32_e32 v188, v180, v181
	v_add_f32_e32 v188, v188, v182
	v_mfma_f32_16x16x4_f32 v[4:7], v36, v45, v[4:7]
	v_add_f32_e32 v188, v188, v183
	v_add_f32_e32 v188, v188, v184
	v_add_f32_e32 v188, v188, v185
	v_mfma_f32_16x16x4_f32 v[0:3], v37, v46, v[0:3]
	v_add_f32_e32 v188, v188, v186
	v_add_f32_e32 v188, v188, v187
	v_mul_f32_e32 v189, v188, v188
	v_mfma_f32_16x16x4_f32 v[4:7], v37, v47, v[4:7]
	v_cvt_pk_bf16_f32 v192, v188, v129
	v_mov_b32_e32 v193, v188
	v_mov_b32_e32 v194, v189
	v_mfma_f32_16x16x4_f32 v[0:3], v38, v48, v[0:3]
	global_store_short v135, v192, s[10:11]
	s_nop 1
	v_permlane16_swap_b32_e32 v188, v193
	v_permlane16_swap_b32_e32 v189, v194
	v_mfma_f32_16x16x4_f32 v[4:7], v38, v49, v[4:7]
	v_add_f32_e32 v188, v188, v193
	v_add_f32_e32 v189, v189, v194
	s_nop 1
	v_add_f32_dpp v188, v188, v188 row_ror:8 row_mask:0xf bank_mask:0xf
	v_mfma_f32_16x16x4_f32 v[0:3], v39, v50, v[0:3]
	v_add_f32_dpp v189, v189, v189 row_ror:8 row_mask:0xf bank_mask:0xf
	s_nop 1
	v_add_f32_dpp v188, v188, v188 row_ror:4 row_mask:0xf bank_mask:0xf
	v_add_f32_dpp v189, v189, v189 row_ror:4 row_mask:0xf bank_mask:0xf
	v_mfma_f32_16x16x4_f32 v[4:7], v39, v51, v[4:7]
	s_nop 1
	v_add_f32_dpp v188, v188, v188 row_ror:2 row_mask:0xf bank_mask:0xf
	v_add_f32_dpp v189, v189, v189 row_ror:2 row_mask:0xf bank_mask:0xf
	s_nop 1
	v_add_f32_dpp v188, v188, v188 row_ror:1 row_mask:0xf bank_mask:0xf
	s_nop 7
	v_pk_mul_f32 v[0:1], v[0:1], v[64:65]
	v_pk_mul_f32 v[2:3], v[2:3], v[66:67]
	v_pk_mul_f32 v[4:5], v[4:5], v[64:65]
	v_pk_mul_f32 v[6:7], v[6:7], v[66:67]
	s_nop 1
	v_mfma_f32_16x16x4_f32 v[16:19], v32, v28, 0
	s_waitcnt vmcnt(25)
	v_lshlrev_b32_e32 v20, 16, v100
	v_and_b32_e32 v21, s69, v100
	v_add_f32_dpp v189, v189, v189 row_ror:1 row_mask:0xf bank_mask:0xf
	v_mfma_f32_16x16x4_f32 v[8:11], v0, v28, 0
	v_lshlrev_b32_e32 v22, 16, v101
	v_and_b32_e32 v23, s69, v101
	v_lshlrev_b32_e32 v24, 16, v102
	v_mov_b32_e32 v190, 0
	v_mfma_f32_16x16x4_f32 v[16:19], v33, v29, v[16:19]
	v_and_b32_e32 v25, s69, v102
	v_lshlrev_b32_e32 v26, 16, v103
	v_and_b32_e32 v27, s69, v103
	v_mov_b32_e32 v191, 0
	v_mfma_f32_16x16x4_f32 v[12:15], v4, v28, 0
	v_lshlrev_b32_e32 v44, 16, v104
	v_and_b32_e32 v45, s69, v104
	v_lshlrev_b32_e32 v46, 16, v105
	s_nop 0
	s_mov_b64 exec, s[18:19]
	global_store_dwordx4 v139, v[188:191], s[12:13]
	s_mov_b64 exec, -1
	s_cmp_eq_u32 s15, 512
	s_cselect_b32 s20, 0, 0x10000
	s_cselect_b32 s21, 0, 0x1000
	s_add_u32 s10, s10, s20
	s_addc_u32 s11, s11, 0
	s_add_u32 s12, s12, s21
	s_addc_u32 s13, s13, 0
	v_mfma_f32_16x16x4_f32 v[16:19], v34, v30, v[16:19]
	v_and_b32_e32 v47, s69, v105
	v_lshlrev_b32_e32 v48, 16, v106
	v_and_b32_e32 v49, s69, v106
	v_mfma_f32_16x16x4_f32 v[8:11], v1, v29, v[8:11]
	v_lshlrev_b32_e32 v50, 16, v107
	v_and_b32_e32 v51, s69, v107
	global_load_dwordx2 v[100:101], v130, s[8:9]
	global_load_dwordx2 v[102:103], v130, s[8:9] offset:1024
	global_load_dword v104, v131, s[8:9]
	global_load_dword v105, v132, s[8:9]
	global_load_dword v106, v133, s[8:9]
	global_load_dword v107, v134, s[8:9]
	s_add_u32 s8, s8, 0x34000
	s_addc_u32 s9, s9, 0
	v_mfma_f32_16x16x4_f32 v[16:19], v35, v31, v[16:19]
	v_mul_f32_e32 v24, 0x3fb8aa3b, v24
	v_mul_f32_e32 v25, 0x3fb8aa3b, v25
	v_mul_f32_e32 v26, 0x3fb8aa3b, v26
	v_mfma_f32_16x16x4_f32 v[12:15], v5, v29, v[12:15]
	v_mul_f32_e32 v27, 0x3fb8aa3b, v27
	v_add_f32_dpp v80, v24, v24 row_shl:1 row_mask:0xf bank_mask:0xf bound_ctrl:0
	v_add_f32_dpp v81, v25, v25 row_shl:1 row_mask:0xf bank_mask:0xf bound_ctrl:0
	v_mfma_f32_16x16x4_f32 v[8:11], v2, v30, v[8:11]
	v_add_f32_dpp v82, v26, v26 row_shl:1 row_mask:0xf bank_mask:0xf bound_ctrl:0
	v_add_f32_dpp v83, v27, v27 row_shl:1 row_mask:0xf bank_mask:0xf bound_ctrl:0
	v_add_f32_dpp v80, v80, v80 row_shl:2 row_mask:0xf bank_mask:0xf bound_ctrl:0
	v_mfma_f32_16x16x4_f32 v[12:15], v6, v30, v[12:15]
	v_add_f32_dpp v81, v81, v81 row_shl:2 row_mask:0xf bank_mask:0xf bound_ctrl:0
	v_add_f32_dpp v82, v82, v82 row_shl:2 row_mask:0xf bank_mask:0xf bound_ctrl:0
	v_add_f32_dpp v83, v83, v83 row_shl:2 row_mask:0xf bank_mask:0xf bound_ctrl:0
	v_mfma_f32_16x16x4_f32 v[8:11], v3, v31, v[8:11]
	v_add_f32_dpp v80, v80, v80 row_shl:4 row_mask:0xf bank_mask:0xf bound_ctrl:0
	v_add_f32_dpp v81, v81, v81 row_shl:4 row_mask:0xf bank_mask:0xf bound_ctrl:0
	v_add_f32_dpp v82, v82, v82 row_shl:4 row_mask:0xf bank_mask:0xf bound_ctrl:0
	v_mfma_f32_16x16x4_f32 v[12:15], v7, v31, v[12:15]
	v_add_f32_dpp v83, v83, v83 row_shl:4 row_mask:0xf bank_mask:0xf bound_ctrl:0
	v_add_f32_dpp v80, v80, v80 row_shl:8 row_mask:0xf bank_mask:0xf bound_ctrl:0
	v_add_f32_dpp v81, v81, v81 row_shl:8 row_mask:0xf bank_mask:0xf bound_ctrl:0
	v_pk_mul_f32 v[16:17], v[16:17], v[74:75]
	v_pk_mul_f32 v[18:19], v[18:19], v[76:77]
	s_nop 1
	v_permlane16_swap_b32_e32 v16, v17
	v_permlane16_swap_b32_e32 v18, v19
	s_nop 1
	v_permlane32_swap_b32_e32 v16, v18
	v_permlane32_swap_b32_e32 v17, v19
	s_nop 1
	v_mfma_f32_16x16x4_f32 v[8:11], v52, v16, v[8:11]
	v_add_f32_dpp v82, v82, v82 row_shl:8 row_mask:0xf bank_mask:0xf bound_ctrl:0
	v_add_f32_dpp v83, v83, v83 row_shl:8 row_mask:0xf bank_mask:0xf bound_ctrl:0
	v_exp_f32_e32 v84, v24
	v_exp_f32_e32 v85, v25
	v_exp_f32_e32 v86, v26
	v_mfma_f32_16x16x4_f32 v[12:15], v53, v16, v[12:15]
	v_exp_f32_e32 v87, v27
	ds_swizzle_b32 v96, v80 offset:swizzle(BITMASK_PERM,"p0000")
	ds_swizzle_b32 v97, v81 offset:swizzle(BITMASK_PERM,"p0000")
	ds_swizzle_b32 v98, v82 offset:swizzle(BITMASK_PERM,"p0000")
	ds_swizzle_b32 v99, v83 offset:swizzle(BITMASK_PERM,"p0000")
	v_mfma_f32_16x16x4_f32 v[8:11], v54, v17, v[8:11]
	v_sub_f32_e32 v88, v80, v24
	v_sub_f32_e32 v89, v81, v25
	v_sub_f32_e32 v90, v82, v26
	v_sub_f32_e32 v91, v83, v27
	v_max_f32_e32 v88, 0xc2fc0000, v88
	v_mfma_f32_16x16x4_f32 v[12:15], v55, v17, v[12:15]
	v_max_f32_e32 v89, 0xc2fc0000, v89
	v_max_f32_e32 v90, 0xc2fc0000, v90
	v_max_f32_e32 v91, 0xc2fc0000, v91
	v_sub_f32_e32 v84, 1.0, v84
	v_sub_f32_e32 v85, 1.0, v85
	v_mfma_f32_16x16x4_f32 v[8:11], v56, v18, v[8:11]
	v_sub_f32_e32 v86, 1.0, v86
	v_sub_f32_e32 v87, 1.0, v87
	v_exp_f32_e64 v92, -v88
	v_exp_f32_e64 v93, -v89
	v_exp_f32_e64 v94, -v90
	v_mfma_f32_16x16x4_f32 v[12:15], v57, v18, v[12:15]
	v_exp_f32_e64 v95, -v91
	v_exp_f32_e32 v88, v88
	v_exp_f32_e32 v89, v89
	v_exp_f32_e32 v90, v90
	v_exp_f32_e32 v91, v91
	v_mfma_f32_16x16x4_f32 v[8:11], v58, v19, v[8:11]
	s_waitcnt lgkmcnt(0)
	v_exp_f32_e32 v60, v96
	v_exp_f32_e32 v61, v97
	v_exp_f32_e32 v62, v98
	v_exp_f32_e32 v63, v99
	v_mfma_f32_16x16x4_f32 v[12:15], v59, v19, v[12:15]
	v_mul_f32_e32 v24, v84, v88
	v_mul_f32_e32 v25, v85, v89
	v_mul_f32_e32 v26, v86, v90
	v_mul_f32_e32 v27, v87, v91
	v_mul_f32_e32 v20, v20, v92
	v_mul_f32_e32 v21, v21, v93
	v_mul_f32_e32 v22, v22, v94
	v_mul_f32_e32 v23, v23, v95
	ds_write_b128 v153, v[24:27]
	ds_read_b32 v36, v154 offset:0
	ds_read_b32 v37, v154 offset:320
	ds_read_b32 v38, v154 offset:640
	ds_read_b32 v39, v154 offset:960
	s_waitcnt lgkmcnt(0)
	s_nop 7
	s_nop 1
	ds_write2_b32 v152, v8, v12 offset0:0 offset1:1
	ds_write2_b32 v152, v9, v13 offset0:2 offset1:3
	ds_write2_b32 v152, v10, v14 offset0:4 offset1:5
	ds_write2_b32 v152, v11, v15 offset0:6 offset1:7
	s_sub_u32 s15, s15, 1
	s_waitcnt lgkmcnt(0)
	s_barrier
	s_cmp_lg_u32 s15, 0
	s_cbranch_scc1 .Lgla_loop_hgrn
	s_branch .Lgla_tail
.Lgla_ret_setup:
	v_log_f32_e32 v125, v195
	v_add_u32_e32 v126, 1, v157
	v_cvt_f32_i32_e32 v126, v126
	v_mul_f32_e32 v126, v126, v125
	v_exp_f32_e32 v68, v126
	s_nop 0
	v_mov_b32_e32 v69, v68
	v_sub_u32_e32 v126, 15, v158
	v_cvt_f32_i32_e32 v126, v126
	v_mul_f32_e32 v126, v126, v125
	v_exp_f32_e32 v70, v126
	v_sub_u32_e32 v126, 11, v158
	v_cvt_f32_i32_e32 v126, v126
	v_mul_f32_e32 v126, v126, v125
	v_exp_f32_e32 v71, v126
	v_sub_u32_e32 v126, 7, v158
	v_cvt_f32_i32_e32 v126, v126
	v_mul_f32_e32 v126, v126, v125
	v_exp_f32_e32 v72, v126
	v_sub_u32_e32 v126, 3, v158
	v_cvt_f32_i32_e32 v126, v126
	v_mul_f32_e32 v126, v126, v125
	v_exp_f32_e32 v73, v126
	v_lshl_add_u32 v127, v158, 2, 0
	v_add_u32_e32 v126, 1, v127
	v_cvt_f32_i32_e32 v126, v126
	v_mul_f32_e64 v126, -v126, v125
	v_exp_f32_e32 v126, v126
	v_cmp_le_u32_e32 vcc, v127, v157
	s_nop 1
	v_cndmask_b32_e32 v74, 0, v126, vcc
	v_lshl_add_u32 v127, v158, 2, 1
	v_add_u32_e32 v126, 1, v127
	v_cvt_f32_i32_e32 v126, v126
	v_mul_f32_e64 v126, -v126, v125
	v_exp_f32_e32 v126, v126
	v_cmp_le_u32_e32 vcc, v127, v157
	s_nop 1
	v_cndmask_b32_e32 v75, 0, v126, vcc
	v_lshl_add_u32 v127, v158, 2, 2
	v_add_u32_e32 v126, 1, v127
	v_cvt_f32_i32_e32 v126, v126
	v_mul_f32_e64 v126, -v126, v125
	v_exp_f32_e32 v126, v126
	v_cmp_le_u32_e32 vcc, v127, v157
	s_nop 1
	v_cndmask_b32_e32 v76, 0, v126, vcc
	v_lshl_add_u32 v127, v158, 2, 3
	v_add_u32_e32 v126, 1, v127
	v_cvt_f32_i32_e32 v126, v126
	v_mul_f32_e64 v126, -v126, v125
	v_exp_f32_e32 v126, v126
	v_cmp_le_u32_e32 vcc, v127, v157
	s_nop 1
	v_cndmask_b32_e32 v77, 0, v126, vcc
	v_mul_f32_e32 v78, v195, v195
	v_mul_f32_e32 v78, v78, v78
	v_mul_f32_e32 v78, v78, v78
	v_mul_f32_e32 v78, v78, v78
	v_mov_b32_e32 v79, v78
	s_waitcnt vmcnt(0)
	v_lshlrev_b32_e32 v20, 16, v100
	v_and_b32_e32 v21, s69, v100
	v_lshlrev_b32_e32 v22, 16, v101
	v_and_b32_e32 v23, s69, v101
	v_lshlrev_b32_e32 v24, 16, v102
	v_and_b32_e32 v25, s69, v102
	v_lshlrev_b32_e32 v26, 16, v103
	v_and_b32_e32 v27, s69, v103
	v_lshlrev_b32_e32 v44, 16, v104
	v_and_b32_e32 v45, s69, v104
	v_lshlrev_b32_e32 v46, 16, v105
	v_and_b32_e32 v47, s69, v105
	v_lshlrev_b32_e32 v48, 16, v106
	v_and_b32_e32 v49, s69, v106
	v_lshlrev_b32_e32 v50, 16, v107
	v_and_b32_e32 v51, s69, v107
	v_pk_mul_f32 v[20:21], v[20:21], v[68:69]
	v_pk_mul_f32 v[22:23], v[22:23], v[68:69]
	ds_write_b128 v153, v[24:27]
	ds_read_b32 v36, v154 offset:0
	ds_read_b32 v37, v154 offset:320
	ds_read_b32 v38, v154 offset:640
	ds_read_b32 v39, v154 offset:960
	s_waitcnt lgkmcnt(0)
	v_mul_f32_e32 v36, v36, v70
	v_mul_f32_e32 v37, v37, v71
	v_mul_f32_e32 v38, v38, v72
	v_mul_f32_e32 v39, v39, v73
	global_load_dword v124, v130, s[8:9]
	global_load_dword v124, v130, s[8:9]
	global_load_dwordx2 v[108:109], v130, s[8:9]
	global_load_dwordx2 v[110:111], v130, s[8:9] offset:1024
	global_load_dword v112, v131, s[8:9]
	global_load_dword v113, v132, s[8:9]
	global_load_dword v114, v133, s[8:9]
	global_load_dword v115, v134, s[8:9]
	s_add_u32 s8, s8, 0x34000
	s_addc_u32 s9, s9, 0
	global_load_dword v124, v130, s[8:9]
	global_load_dword v124, v130, s[8:9]
	global_load_dwordx2 v[116:117], v130, s[8:9]
	global_load_dwordx2 v[118:119], v130, s[8:9] offset:1024
	global_load_dword v120, v131, s[8:9]
	global_load_dword v121, v132, s[8:9]
	global_load_dword v122, v133, s[8:9]
	global_load_dword v123, v134, s[8:9]
	s_add_u32 s8, s8, 0x34000
	s_addc_u32 s9, s9, 0
	global_load_dword v124, v130, s[8:9]
	global_load_dword v124, v130, s[8:9]
	global_load_dwordx2 v[140:141], v130, s[8:9]
	global_load_dwordx2 v[142:143], v130, s[8:9] offset:1024
	global_load_dword v144, v131, s[8:9]
	global_load_dword v145, v132, s[8:9]
	global_load_dword v146, v133, s[8:9]
	global_load_dword v147, v134, s[8:9]
	s_add_u32 s8, s8, 0x34000
	s_addc_u32 s9, s9, 0
	global_load_dword v124, v130, s[8:9]
	global_load_dword v124, v130, s[8:9]
	global_load_dwordx2 v[100:101], v130, s[8:9]
	global_load_dwordx2 v[102:103], v130, s[8:9] offset:1024
	global_load_dword v104, v131, s[8:9]
	global_load_dword v105, v132, s[8:9]
	global_load_dword v106, v133, s[8:9]
	global_load_dword v107, v134, s[8:9]
	s_add_u32 s8, s8, 0x34000
	s_addc_u32 s9, s9, 0
	s_waitcnt lgkmcnt(0)
	s_barrier
	.p2align 6
.Lgla_loop_ret:
	ds_read2_b32 v[180:181], v149 offset0:0 offset1:32
	ds_read2_b32 v[182:183], v149 offset0:64 offset1:96
	ds_read2_b32 v[184:185], v149 offset0:128 offset1:160
	ds_read2_b32 v[186:187], v149 offset0:192 offset1:224
	v_mfma_f32_16x16x4_f32 v[0:3], v40, v52, v[0:3]
	s_waitcnt lgkmcnt(0)
	v_add_f32_e32 v188, v180, v181
	v_add_f32_e32 v188, v188, v182
	v_mfma_f32_16x16x4_f32 v[4:7], v40, v53, v[4:7]
	v_add_f32_e32 v188, v188, v183
	v_add_f32_e32 v188, v188, v184
	v_add_f32_e32 v188, v188, v185
	v_mfma_f32_16x16x4_f32 v[0:3], v41, v54, v[0:3]
	v_add_f32_e32 v188, v188, v186
	v_add_f32_e32 v188, v188, v187
	v_mul_f32_e32 v189, v188, v188
	v_mfma_f32_16x16x4_f32 v[4:7], v41, v55, v[4:7]
	v_cvt_pk_bf16_f32 v192, v188, v129
	v_mov_b32_e32 v193, v188
	v_mov_b32_e32 v194, v189
	v_mfma_f32_16x16x4_f32 v[0:3], v42, v56, v[0:3]
	global_store_short v135, v192, s[10:11]
	s_nop 1
	v_permlane16_swap_b32_e32 v188, v193
	v_permlane16_swap_b32_e32 v189, v194
	v_mfma_f32_16x16x4_f32 v[4:7], v42, v57, v[4:7]
	v_add_f32_e32 v188, v188, v193
	v_add_f32_e32 v189, v189, v194
	s_nop 1
	v_add_f32_dpp v188, v188, v188 row_ror:8 row_mask:0xf bank_mask:0xf
	v_mfma_f32_16x16x4_f32 v[0:3], v43, v58, v[0:3]
	v_add_f32_dpp v189, v189, v189 row_ror:8 row_mask:0xf bank_mask:0xf
	s_nop 1
	v_add_f32_dpp v188, v188, v188 row_ror:4 row_mask:0xf bank_mask:0xf
	v_add_f32_dpp v189, v189, v189 row_ror:4 row_mask:0xf bank_mask:0xf
	v_mfma_f32_16x16x4_f32 v[4:7], v43, v59, v[4:7]
	s_nop 1
	v_add_f32_dpp v188, v188, v188 row_ror:2 row_mask:0xf bank_mask:0xf
	v_add_f32_dpp v189, v189, v189 row_ror:2 row_mask:0xf bank_mask:0xf
	s_nop 1
	v_add_f32_dpp v188, v188, v188 row_ror:1 row_mask:0xf bank_mask:0xf
	s_nop 7
	s_nop 1
	v_mfma_f32_16x16x4_f32 v[16:19], v24, v20, 0
	s_waitcnt vmcnt(25)
	v_lshlrev_b32_e32 v28, 16, v108
	v_and_b32_e32 v29, s69, v108
	v_add_f32_dpp v189, v189, v189 row_ror:1 row_mask:0xf bank_mask:0xf
	v_mfma_f32_16x16x4_f32 v[8:11], v0, v20, 0
	v_lshlrev_b32_e32 v30, 16, v109
	v_and_b32_e32 v31, s69, v109
	v_lshlrev_b32_e32 v32, 16, v110
	v_mov_b32_e32 v190, 0
	v_mfma_f32_16x16x4_f32 v[16:19], v25, v21, v[16:19]
	v_and_b32_e32 v33, s69, v110
	v_lshlrev_b32_e32 v34, 16, v111
	v_and_b32_e32 v35, s69, v111
	v_mov_b32_e32 v191, 0
	v_mfma_f32_16x16x4_f32 v[12:15], v4, v20, 0
	v_lshlrev_b32_e32 v52, 16, v112
	v_and_b32_e32 v53, s69, v112
	v_lshlrev_b32_e32 v54, 16, v113
	s_nop 0
	s_mov_b64 exec, s[18:19]
	global_store_dwordx4 v139, v[188:191], s[12:13]
	s_mov_b64 exec, -1
	s_cmp_eq_u32 s15, 512
	s_cselect_b32 s20, 0, 0x10000
	s_cselect_b32 s21, 0, 0x1000
	s_add_u32 s10, s10, s20
	s_addc_u32 s11, s11, 0
	s_add_u32 s12, s12, s21
	s_addc_u32 s13, s13, 0
	v_mfma_f32_16x16x4_f32 v[16:19], v26, v22, v[16:19]
	v_and_b32_e32 v55, s69, v113
	v_lshlrev_b32_e32 v56, 16, v114
	v_and_b32_e32 v57, s69, v114
	v_mfma_f32_16x16x4_f32 v[8:11], v1, v21, v[8:11]
	v_lshlrev_b32_e32 v58, 16, v115
	v_and_b32_e32 v59, s69, v115
	global_load_dwordx2 v[108:109], v130, s[8:9]
	global_load_dwordx2 v[110:111], v130, s[8:9] offset:1024
	global_load_dword v112, v131, s[8:9]
	global_load_dword v113, v132, s[8:9]
	global_load_dword v114, v133, s[8:9]
	global_load_dword v115, v134, s[8:9]
	s_add_u32 s8, s8, 0x34000
	s_addc_u32 s9, s9, 0
	v_mfma_f32_16x16x4_f32 v[16:19], v27, v23, v[16:19]
	v_pk_mul_f32 v[28:29], v[28:29], v[68:69]
	v_pk_mul_f32 v[30:31], v[30:31], v[68:69]
	ds_write_b128 v153, v[32:35]
	v_mfma_f32_16x16x4_f32 v[12:15], v5, v21, v[12:15]
	ds_read_b32 v40, v154 offset:0
	ds_read_b32 v41, v154 offset:320
	ds_read_b32 v42, v154 offset:640
	v_mfma_f32_16x16x4_f32 v[8:11], v2, v22, v[8:11]
	ds_read_b32 v43, v154 offset:960
	s_waitcnt lgkmcnt(0)
	v_mul_f32_e32 v40, v40, v70
	v_mfma_f32_16x16x4_f32 v[12:15], v6, v22, v[12:15]
	v_mul_f32_e32 v41, v41, v71
	v_mul_f32_e32 v42, v42, v72
	v_mul_f32_e32 v43, v43, v73
	v_mfma_f32_16x16x4_f32 v[8:11], v3, v23, v[8:11]
	v_mfma_f32_16x16x4_f32 v[12:15], v7, v23, v[12:15]
	v_pk_mul_f32 v[0:1], v[0:1], v[78:79]
	v_pk_mul_f32 v[2:3], v[2:3], v[78:79]
	v_pk_mul_f32 v[4:5], v[4:5], v[78:79]
	v_pk_mul_f32 v[6:7], v[6:7], v[78:79]
	v_pk_mul_f32 v[16:17], v[16:17], v[74:75]
	v_pk_mul_f32 v[18:19], v[18:19], v[76:77]
	s_nop 1
	v_permlane16_swap_b32_e32 v16, v17
	v_permlane16_swap_b32_e32 v18, v19
	s_nop 1
	v_permlane32_swap_b32_e32 v16, v18
	v_permlane32_swap_b32_e32 v17, v19
	s_nop 1
	v_mfma_f32_16x16x4_f32 v[8:11], v44, v16, v[8:11]
	v_mfma_f32_16x16x4_f32 v[12:15], v45, v16, v[12:15]
	v_mfma_f32_16x16x4_f32 v[8:11], v46, v17, v[8:11]
	v_mfma_f32_16x16x4_f32 v[12:15], v47, v17, v[12:15]
	v_mfma_f32_16x16x4_f32 v[8:11], v48, v18, v[8:11]
	v_mfma_f32_16x16x4_f32 v[12:15], v49, v18, v[12:15]
	v_mfma_f32_16x16x4_f32 v[8:11], v50, v19, v[8:11]
	v_mfma_f32_16x16x4_f32 v[12:15], v51, v19, v[12:15]
	s_nop 7
	s_nop 1
	ds_write2_b32 v150, v8, v12 offset0:0 offset1:1
	ds_write2_b32 v150, v9, v13 offset0:2 offset1:3
	ds_write2_b32 v150, v10, v14 offset0:4 offset1:5
	ds_write2_b32 v150, v11, v15 offset0:6 offset1:7
	s_sub_u32 s15, s15, 1
	s_waitcnt lgkmcnt(0)
	s_barrier
	ds_read2_b32 v[180:181], v148 offset0:0 offset1:32
	ds_read2_b32 v[182:183], v148 offset0:64 offset1:96
	ds_read2_b32 v[184:185], v148 offset0:128 offset1:160
	ds_read2_b32 v[186:187], v148 offset0:192 offset1:224
	v_mfma_f32_16x16x4_f32 v[0:3], v36, v44, v[0:3]
	s_waitcnt lgkmcnt(0)
	v_add_f32_e32 v188, v180, v181
	v_add_f32_e32 v188, v188, v182
	v_mfma_f32_16x16x4_f32 v[4:7], v36, v45, v[4:7]
	v_add_f32_e32 v188, v188, v183
	v_add_f32_e32 v188, v188, v184
	v_add_f32_e32 v188, v188, v185
	v_mfma_f32_16x16x4_f32 v[0:3], v37, v46, v[0:3]
	v_add_f32_e32 v188, v188, v186
	v_add_f32_e32 v188, v188, v187
	v_mul_f32_e32 v189, v188, v188
	v_mfma_f32_16x16x4_f32 v[4:7], v37, v47, v[4:7]
	v_cvt_pk_bf16_f32 v192, v188, v129
	v_mov_b32_e32 v193, v188
	v_mov_b32_e32 v194, v189
	v_mfma_f32_16x16x4_f32 v[0:3], v38, v48, v[0:3]
	global_store_short v135, v192, s[10:11]
	s_nop 1
	v_permlane16_swap_b32_e32 v188, v193
	v_permlane16_swap_b32_e32 v189, v194
	v_mfma_f32_16x16x4_f32 v[4:7], v38, v49, v[4:7]
	v_add_f32_e32 v188, v188, v193
	v_add_f32_e32 v189, v189, v194
	s_nop 1
	v_add_f32_dpp v188, v188, v188 row_ror:8 row_mask:0xf bank_mask:0xf
	v_mfma_f32_16x16x4_f32 v[0:3], v39, v50, v[0:3]
	v_add_f32_dpp v189, v189, v189 row_ror:8 row_mask:0xf bank_mask:0xf
	s_nop 1
	v_add_f32_dpp v188, v188, v188 row_ror:4 row_mask:0xf bank_mask:0xf
	v_add_f32_dpp v189, v189, v189 row_ror:4 row_mask:0xf bank_mask:0xf
	v_mfma_f32_16x16x4_f32 v[4:7], v39, v51, v[4:7]
	s_nop 1
	v_add_f32_dpp v188, v188, v188 row_ror:2 row_mask:0xf bank_mask:0xf
	v_add_f32_dpp v189, v189, v189 row_ror:2 row_mask:0xf bank_mask:0xf
	s_nop 1
	v_add_f32_dpp v188, v188, v188 row_ror:1 row_mask:0xf bank_mask:0xf
	s_nop 7
	s_nop 1
	v_mfma_f32_16x16x4_f32 v[16:19], v32, v28, 0
	s_waitcnt vmcnt(25)
	v_lshlrev_b32_e32 v20, 16, v116
	v_and_b32_e32 v21, s69, v116
	v_add_f32_dpp v189, v189, v189 row_ror:1 row_mask:0xf bank_mask:0xf
	v_mfma_f32_16x16x4_f32 v[8:11], v0, v28, 0
	v_lshlrev_b32_e32 v22, 16, v117
	v_and_b32_e32 v23, s69, v117
	v_lshlrev_b32_e32 v24, 16, v118
	v_mov_b32_e32 v190, 0
	v_mfma_f32_16x16x4_f32 v[16:19], v33, v29, v[16:19]
	v_and_b32_e32 v25, s69, v118
	v_lshlrev_b32_e32 v26, 16, v119
	v_and_b32_e32 v27, s69, v119
	v_mov_b32_e32 v191, 0
	v_mfma_f32_16x16x4_f32 v[12:15], v4, v28, 0
	v_lshlrev_b32_e32 v44, 16, v120
	v_and_b32_e32 v45, s69, v120
	v_lshlrev_b32_e32 v46, 16, v121
	s_nop 0
	s_mov_b64 exec, s[18:19]
	global_store_dwordx4 v139, v[188:191], s[12:13]
	s_mov_b64 exec, -1
	s_cmp_eq_u32 s15, 512
	s_cselect_b32 s20, 0, 0x10000
	s_cselect_b32 s21, 0, 0x1000
	s_add_u32 s10, s10, s20
	s_addc_u32 s11, s11, 0
	s_add_u32 s12, s12, s21
	s_addc_u32 s13, s13, 0
	v_mfma_f32_16x16x4_f32 v[16:19], v34, v30, v[16:19]
	v_and_b32_e32 v47, s69, v121
	v_lshlrev_b32_e32 v48, 16, v122
	v_and_b32_e32 v49, s69, v122
	v_mfma_f32_16x16x4_f32 v[8:11], v1, v29, v[8:11]
	v_lshlrev_b32_e32 v50, 16, v123
	v_and_b32_e32 v51, s69, v123
	global_load_dwordx2 v[116:117], v130, s[8:9]
	global_load_dwordx2 v[118:119], v130, s[8:9] offset:1024
	global_load_dword v120, v131, s[8:9]
	global_load_dword v121, v132, s[8:9]
	global_load_dword v122, v133, s[8:9]
	global_load_dword v123, v134, s[8:9]
	s_add_u32 s8, s8, 0x34000
	s_addc_u32 s9, s9, 0
	v_mfma_f32_16x16x4_f32 v[16:19], v35, v31, v[16:19]
	v_pk_mul_f32 v[20:21], v[20:21], v[68:69]
	v_pk_mul_f32 v[22:23], v[22:23], v[68:69]
	ds_write_b128 v153, v[24:27]
	v_mfma_f32_16x16x4_f32 v[12:15], v5, v29, v[12:15]
	ds_read_b32 v36, v154 offset:0
	ds_read_b32 v37, v154 offset:320
	ds_read_b32 v38, v154 offset:640
	v_mfma_f32_16x16x4_f32 v[8:11], v2, v30, v[8:11]
	ds_read_b32 v39, v154 offset:960
	s_waitcnt lgkmcnt(0)
	v_mul_f32_e32 v36, v36, v70
	v_mfma_f32_16x16x4_f32 v[12:15], v6, v30, v[12:15]
	v_mul_f32_e32 v37, v37, v71
	v_mul_f32_e32 v38, v38, v72
	v_mul_f32_e32 v39, v39, v73
	v_mfma_f32_16x16x4_f32 v[8:11], v3, v31, v[8:11]
	v_mfma_f32_16x16x4_f32 v[12:15], v7, v31, v[12:15]
	v_pk_mul_f32 v[0:1], v[0:1], v[78:79]
	v_pk_mul_f32 v[2:3], v[2:3], v[78:79]
	v_pk_mul_f32 v[4:5], v[4:5], v[78:79]
	v_pk_mul_f32 v[6:7], v[6:7], v[78:79]
	v_pk_mul_f32 v[16:17], v[16:17], v[74:75]
	v_pk_mul_f32 v[18:19], v[18:19], v[76:77]
	s_nop 1
	v_permlane16_swap_b32_e32 v16, v17
	v_permlane16_swap_b32_e32 v18, v19
	s_nop 1
	v_permlane32_swap_b32_e32 v16, v18
	v_permlane32_swap_b32_e32 v17, v19
	s_nop 1
	v_mfma_f32_16x16x4_f32 v[8:11], v52, v16, v[8:11]
	v_mfma_f32_16x16x4_f32 v[12:15], v53, v16, v[12:15]
	v_mfma_f32_16x16x4_f32 v[8:11], v54, v17, v[8:11]
	v_mfma_f32_16x16x4_f32 v[12:15], v55, v17, v[12:15]
	v_mfma_f32_16x16x4_f32 v[8:11], v56, v18, v[8:11]
	v_mfma_f32_16x16x4_f32 v[12:15], v57, v18, v[12:15]
	v_mfma_f32_16x16x4_f32 v[8:11], v58, v19, v[8:11]
	v_mfma_f32_16x16x4_f32 v[12:15], v59, v19, v[12:15]
	s_nop 7
	s_nop 1
	ds_write2_b32 v152, v8, v12 offset0:0 offset1:1
	ds_write2_b32 v152, v9, v13 offset0:2 offset1:3
	ds_write2_b32 v152, v10, v14 offset0:4 offset1:5
	ds_write2_b32 v152, v11, v15 offset0:6 offset1:7
	s_sub_u32 s15, s15, 1
	s_waitcnt lgkmcnt(0)
	s_barrier
	ds_read2_b32 v[180:181], v149 offset0:0 offset1:32
	ds_read2_b32 v[182:183], v149 offset0:64 offset1:96
	ds_read2_b32 v[184:185], v149 offset0:128 offset1:160
	ds_read2_b32 v[186:187], v149 offset0:192 offset1:224
	v_mfma_f32_16x16x4_f32 v[0:3], v40, v52, v[0:3]
	s_waitcnt lgkmcnt(0)
	v_add_f32_e32 v188, v180, v181
	v_add_f32_e32 v188, v188, v182
	v_mfma_f32_16x16x4_f32 v[4:7], v40, v53, v[4:7]
	v_add_f32_e32 v188, v188, v183
	v_add_f32_e32 v188, v188, v184
	v_add_f32_e32 v188, v188, v185
	v_mfma_f32_16x16x4_f32 v[0:3], v41, v54, v[0:3]
	v_add_f32_e32 v188, v188, v186
	v_add_f32_e32 v188, v188, v187
	v_mul_f32_e32 v189, v188, v188
	v_mfma_f32_16x16x4_f32 v[4:7], v41, v55, v[4:7]
	v_cvt_pk_bf16_f32 v192, v188, v129
	v_mov_b32_e32 v193, v188
	v_mov_b32_e32 v194, v189
	v_mfma_f32_16x16x4_f32 v[0:3], v42, v56, v[0:3]
	global_store_short v135, v192, s[10:11]
	s_nop 1
	v_permlane16_swap_b32_e32 v188, v193
	v_permlane16_swap_b32_e32 v189, v194
	v_mfma_f32_16x16x4_f32 v[4:7], v42, v57, v[4:7]
	v_add_f32_e32 v188, v188, v193
	v_add_f32_e32 v189, v189, v194
	s_nop 1
	v_add_f32_dpp v188, v188, v188 row_ror:8 row_mask:0xf bank_mask:0xf
	v_mfma_f32_16x16x4_f32 v[0:3], v43, v58, v[0:3]
	v_add_f32_dpp v189, v189, v189 row_ror:8 row_mask:0xf bank_mask:0xf
	s_nop 1
	v_add_f32_dpp v188, v188, v188 row_ror:4 row_mask:0xf bank_mask:0xf
	v_add_f32_dpp v189, v189, v189 row_ror:4 row_mask:0xf bank_mask:0xf
	v_mfma_f32_16x16x4_f32 v[4:7], v43, v59, v[4:7]
	s_nop 1
	v_add_f32_dpp v188, v188, v188 row_ror:2 row_mask:0xf bank_mask:0xf
	v_add_f32_dpp v189, v189, v189 row_ror:2 row_mask:0xf bank_mask:0xf
	s_nop 1
	v_add_f32_dpp v188, v188, v188 row_ror:1 row_mask:0xf bank_mask:0xf
	s_nop 7
	s_nop 1
	v_mfma_f32_16x16x4_f32 v[16:19], v24, v20, 0
	s_waitcnt vmcnt(25)
	v_lshlrev_b32_e32 v28, 16, v140
	v_and_b32_e32 v29, s69, v140
	v_add_f32_dpp v189, v189, v189 row_ror:1 row_mask:0xf bank_mask:0xf
	v_mfma_f32_16x16x4_f32 v[8:11], v0, v20, 0
	v_lshlrev_b32_e32 v30, 16, v141
	v_and_b32_e32 v31, s69, v141
	v_lshlrev_b32_e32 v32, 16, v142
	v_mov_b32_e32 v190, 0
	v_mfma_f32_16x16x4_f32 v[16:19], v25, v21, v[16:19]
	v_and_b32_e32 v33, s69, v142
	v_lshlrev_b32_e32 v34, 16, v143
	v_and_b32_e32 v35, s69, v143
	v_mov_b32_e32 v191, 0
	v_mfma_f32_16x16x4_f32 v[12:15], v4, v20, 0
	v_lshlrev_b32_e32 v52, 16, v144
	v_and_b32_e32 v53, s69, v144
	v_lshlrev_b32_e32 v54, 16, v145
	s_nop 0
	s_mov_b64 exec, s[18:19]
	global_store_dwordx4 v139, v[188:191], s[12:13]
	s_mov_b64 exec, -1
	s_cmp_eq_u32 s15, 512
	s_cselect_b32 s20, 0, 0x10000
	s_cselect_b32 s21, 0, 0x1000
	s_add_u32 s10, s10, s20
	s_addc_u32 s11, s11, 0
	s_add_u32 s12, s12, s21
	s_addc_u32 s13, s13, 0
	v_mfma_f32_16x16x4_f32 v[16:19], v26, v22, v[16:19]
	v_and_b32_e32 v55, s69, v145
	v_lshlrev_b32_e32 v56, 16, v146
	v_and_b32_e32 v57, s69, v146
	v_mfma_f32_16x16x4_f32 v[8:11], v1, v21, v[8:11]
	v_lshlrev_b32_e32 v58, 16, v147
	v_and_b32_e32 v59, s69, v147
	global_load_dwordx2 v[140:141], v130, s[8:9]
	global_load_dwordx2 v[142:143], v130, s[8:9] offset:1024
	global_load_dword v144, v131, s[8:9]
	global_load_dword v145, v132, s[8:9]
	global_load_dword v146, v133, s[8:9]
	global_load_dword v147, v134, s[8:9]
	s_add_u32 s8, s8, 0x34000
	s_addc_u32 s9, s9, 0
	v_mfma_f32_16x16x4_f32 v[16:19], v27, v23, v[16:19]
	v_pk_mul_f32 v[28:29], v[28:29], v[68:69]
	v_pk_mul_f32 v[30:31], v[30:31], v[68:69]
	ds_write_b128 v153, v[32:35]
	v_mfma_f32_16x16x4_f32 v[12:15], v5, v21, v[12:15]
	ds_read_b32 v40, v154 offset:0
	ds_read_b32 v41, v154 offset:320
	ds_read_b32 v42, v154 offset:640
	v_mfma_f32_16x16x4_f32 v[8:11], v2, v22, v[8:11]
	ds_read_b32 v43, v154 offset:960
	s_waitcnt lgkmcnt(0)
	v_mul_f32_e32 v40, v40, v70
	v_mfma_f32_16x16x4_f32 v[12:15], v6, v22, v[12:15]
	v_mul_f32_e32 v41, v41, v71
	v_mul_f32_e32 v42, v42, v72
	v_mul_f32_e32 v43, v43, v73
	v_mfma_f32_16x16x4_f32 v[8:11], v3, v23, v[8:11]
	v_mfma_f32_16x16x4_f32 v[12:15], v7, v23, v[12:15]
	v_pk_mul_f32 v[0:1], v[0:1], v[78:79]
	v_pk_mul_f32 v[2:3], v[2:3], v[78:79]
	v_pk_mul_f32 v[4:5], v[4:5], v[78:79]
	v_pk_mul_f32 v[6:7], v[6:7], v[78:79]
	v_pk_mul_f32 v[16:17], v[16:17], v[74:75]
	v_pk_mul_f32 v[18:19], v[18:19], v[76:77]
	s_nop 1
	v_permlane16_swap_b32_e32 v16, v17
	v_permlane16_swap_b32_e32 v18, v19
	s_nop 1
	v_permlane32_swap_b32_e32 v16, v18
	v_permlane32_swap_b32_e32 v17, v19
	s_nop 1
	v_mfma_f32_16x16x4_f32 v[8:11], v44, v16, v[8:11]
	v_mfma_f32_16x16x4_f32 v[12:15], v45, v16, v[12:15]
	v_mfma_f32_16x16x4_f32 v[8:11], v46, v17, v[8:11]
	v_mfma_f32_16x16x4_f32 v[12:15], v47, v17, v[12:15]
	v_mfma_f32_16x16x4_f32 v[8:11], v48, v18, v[8:11]
	v_mfma_f32_16x16x4_f32 v[12:15], v49, v18, v[12:15]
	v_mfma_f32_16x16x4_f32 v[8:11], v50, v19, v[8:11]
	v_mfma_f32_16x16x4_f32 v[12:15], v51, v19, v[12:15]
	s_nop 7
	s_nop 1
	ds_write2_b32 v150, v8, v12 offset0:0 offset1:1
	ds_write2_b32 v150, v9, v13 offset0:2 offset1:3
	ds_write2_b32 v150, v10, v14 offset0:4 offset1:5
	ds_write2_b32 v150, v11, v15 offset0:6 offset1:7
	s_sub_u32 s15, s15, 1
	s_waitcnt lgkmcnt(0)
	s_barrier
	ds_read2_b32 v[180:181], v148 offset0:0 offset1:32
	ds_read2_b32 v[182:183], v148 offset0:64 offset1:96
	ds_read2_b32 v[184:185], v148 offset0:128 offset1:160
	ds_read2_b32 v[186:187], v148 offset0:192 offset1:224
	v_mfma_f32_16x16x4_f32 v[0:3], v36, v44, v[0:3]
	s_waitcnt lgkmcnt(0)
	v_add_f32_e32 v188, v180, v181
	v_add_f32_e32 v188, v188, v182
	v_mfma_f32_16x16x4_f32 v[4:7], v36, v45, v[4:7]
	v_add_f32_e32 v188, v188, v183
	v_add_f32_e32 v188, v188, v184
	v_add_f32_e32 v188, v188, v185
	v_mfma_f32_16x16x4_f32 v[0:3], v37, v46, v[0:3]
	v_add_f32_e32 v188, v188, v186
	v_add_f32_e32 v188, v188, v187
	v_mul_f32_e32 v189, v188, v188
	v_mfma_f32_16x16x4_f32 v[4:7], v37, v47, v[4:7]
	v_cvt_pk_bf16_f32 v192, v188, v129
	v_mov_b32_e32 v193, v188
	v_mov_b32_e32 v194, v189
	v_mfma_f32_16x16x4_f32 v[0:3], v38, v48, v[0:3]
	global_store_short v135, v192, s[10:11]
	s_nop 1
	v_permlane16_swap_b32_e32 v188, v193
	v_permlane16_swap_b32_e32 v189, v194
	v_mfma_f32_16x16x4_f32 v[4:7], v38, v49, v[4:7]
	v_add_f32_e32 v188, v188, v193
	v_add_f32_e32 v189, v189, v194
	s_nop 1
	v_add_f32_dpp v188, v188, v188 row_ror:8 row_mask:0xf bank_mask:0xf
	v_mfma_f32_16x16x4_f32 v[0:3], v39, v50, v[0:3]
	v_add_f32_dpp v189, v189, v189 row_ror:8 row_mask:0xf bank_mask:0xf
	s_nop 1
	v_add_f32_dpp v188, v188, v188 row_ror:4 row_mask:0xf bank_mask:0xf
	v_add_f32_dpp v189, v189, v189 row_ror:4 row_mask:0xf bank_mask:0xf
	v_mfma_f32_16x16x4_f32 v[4:7], v39, v51, v[4:7]
	s_nop 1
	v_add_f32_dpp v188, v188, v188 row_ror:2 row_mask:0xf bank_mask:0xf
	v_add_f32_dpp v189, v189, v189 row_ror:2 row_mask:0xf bank_mask:0xf
	s_nop 1
	v_add_f32_dpp v188, v188, v188 row_ror:1 row_mask:0xf bank_mask:0xf
	s_nop 7
	s_nop 1
	v_mfma_f32_16x16x4_f32 v[16:19], v32, v28, 0
	s_waitcnt vmcnt(25)
	v_lshlrev_b32_e32 v20, 16, v100
	v_and_b32_e32 v21, s69, v100
	v_add_f32_dpp v189, v189, v189 row_ror:1 row_mask:0xf bank_mask:0xf
	v_mfma_f32_16x16x4_f32 v[8:11], v0, v28, 0
	v_lshlrev_b32_e32 v22, 16, v101
	v_and_b32_e32 v23, s69, v101
	v_lshlrev_b32_e32 v24, 16, v102
	v_mov_b32_e32 v190, 0
	v_mfma_f32_16x16x4_f32 v[16:19], v33, v29, v[16:19]
	v_and_b32_e32 v25, s69, v102
	v_lshlrev_b32_e32 v26, 16, v103
	v_and_b32_e32 v27, s69, v103
	v_mov_b32_e32 v191, 0
	v_mfma_f32_16x16x4_f32 v[12:15], v4, v28, 0
	v_lshlrev_b32_e32 v44, 16, v104
	v_and_b32_e32 v45, s69, v104
	v_lshlrev_b32_e32 v46, 16, v105
	s_nop 0
	s_mov_b64 exec, s[18:19]
	global_store_dwordx4 v139, v[188:191], s[12:13]
	s_mov_b64 exec, -1
	s_cmp_eq_u32 s15, 512
	s_cselect_b32 s20, 0, 0x10000
	s_cselect_b32 s21, 0, 0x1000
	s_add_u32 s10, s10, s20
	s_addc_u32 s11, s11, 0
	s_add_u32 s12, s12, s21
	s_addc_u32 s13, s13, 0
	v_mfma_f32_16x16x4_f32 v[16:19], v34, v30, v[16:19]
	v_and_b32_e32 v47, s69, v105
	v_lshlrev_b32_e32 v48, 16, v106
	v_and_b32_e32 v49, s69, v106
	v_mfma_f32_16x16x4_f32 v[8:11], v1, v29, v[8:11]
	v_lshlrev_b32_e32 v50, 16, v107
	v_and_b32_e32 v51, s69, v107
	global_load_dwordx2 v[100:101], v130, s[8:9]
	global_load_dwordx2 v[102:103], v130, s[8:9] offset:1024
	global_load_dword v104, v131, s[8:9]
	global_load_dword v105, v132, s[8:9]
	global_load_dword v106, v133, s[8:9]
	global_load_dword v107, v134, s[8:9]
	s_add_u32 s8, s8, 0x34000
	s_addc_u32 s9, s9, 0
	v_mfma_f32_16x16x4_f32 v[16:19], v35, v31, v[16:19]
	v_pk_mul_f32 v[20:21], v[20:21], v[68:69]
	v_pk_mul_f32 v[22:23], v[22:23], v[68:69]
	ds_write_b128 v153, v[24:27]
	v_mfma_f32_16x16x4_f32 v[12:15], v5, v29, v[12:15]
	ds_read_b32 v36, v154 offset:0
	ds_read_b32 v37, v154 offset:320
	ds_read_b32 v38, v154 offset:640
	v_mfma_f32_16x16x4_f32 v[8:11], v2, v30, v[8:11]
	ds_read_b32 v39, v154 offset:960
	s_waitcnt lgkmcnt(0)
	v_mul_f32_e32 v36, v36, v70
	v_mfma_f32_16x16x4_f32 v[12:15], v6, v30, v[12:15]
	v_mul_f32_e32 v37, v37, v71
	v_mul_f32_e32 v38, v38, v72
	v_mul_f32_e32 v39, v39, v73
	v_mfma_f32_16x16x4_f32 v[8:11], v3, v31, v[8:11]
	v_mfma_f32_16x16x4_f32 v[12:15], v7, v31, v[12:15]
	v_pk_mul_f32 v[0:1], v[0:1], v[78:79]
	v_pk_mul_f32 v[2:3], v[2:3], v[78:79]
	v_pk_mul_f32 v[4:5], v[4:5], v[78:79]
	v_pk_mul_f32 v[6:7], v[6:7], v[78:79]
	v_pk_mul_f32 v[16:17], v[16:17], v[74:75]
	v_pk_mul_f32 v[18:19], v[18:19], v[76:77]
	s_nop 1
	v_permlane16_swap_b32_e32 v16, v17
	v_permlane16_swap_b32_e32 v18, v19
	s_nop 1
	v_permlane32_swap_b32_e32 v16, v18
	v_permlane32_swap_b32_e32 v17, v19
	s_nop 1
	v_mfma_f32_16x16x4_f32 v[8:11], v52, v16, v[8:11]
	v_mfma_f32_16x16x4_f32 v[12:15], v53, v16, v[12:15]
	v_mfma_f32_16x16x4_f32 v[8:11], v54, v17, v[8:11]
	v_mfma_f32_16x16x4_f32 v[12:15], v55, v17, v[12:15]
	v_mfma_f32_16x16x4_f32 v[8:11], v56, v18, v[8:11]
	v_mfma_f32_16x16x4_f32 v[12:15], v57, v18, v[12:15]
	v_mfma_f32_16x16x4_f32 v[8:11], v58, v19, v[8:11]
	v_mfma_f32_16x16x4_f32 v[12:15], v59, v19, v[12:15]
	s_nop 7
	s_nop 1
	ds_write2_b32 v152, v8, v12 offset0:0 offset1:1
	ds_write2_b32 v152, v9, v13 offset0:2 offset1:3
	ds_write2_b32 v152, v10, v14 offset0:4 offset1:5
	ds_write2_b32 v152, v11, v15 offset0:6 offset1:7
	s_sub_u32 s15, s15, 1
	s_waitcnt lgkmcnt(0)
	s_barrier
	s_cmp_lg_u32 s15, 0
	s_cbranch_scc1 .Lgla_loop_ret
.Lgla_tail:
	ds_read2_b32 v[180:181], v149 offset0:0 offset1:32
	ds_read2_b32 v[182:183], v149 offset0:64 offset1:96
	ds_read2_b32 v[184:185], v149 offset0:128 offset1:160
	ds_read2_b32 v[186:187], v149 offset0:192 offset1:224
	s_waitcnt lgkmcnt(0)
	v_add_f32_e32 v188, v180, v181
	v_add_f32_e32 v188, v188, v182
	v_add_f32_e32 v188, v188, v183
	v_add_f32_e32 v188, v188, v184
	v_add_f32_e32 v188, v188, v185
	v_add_f32_e32 v188, v188, v186
	v_add_f32_e32 v188, v188, v187
	v_mul_f32_e32 v189, v188, v188
	v_cvt_pk_bf16_f32 v192, v188, v129
	v_mov_b32_e32 v193, v188
	v_mov_b32_e32 v194, v189
	global_store_short v135, v192, s[10:11]
	s_nop 1
	v_permlane16_swap_b32_e32 v188, v193
	v_permlane16_swap_b32_e32 v189, v194
	v_add_f32_e32 v188, v188, v193
	v_add_f32_e32 v189, v189, v194
	s_nop 1
	v_add_f32_dpp v188, v188, v188 row_ror:8 row_mask:0xf bank_mask:0xf
	v_add_f32_dpp v189, v189, v189 row_ror:8 row_mask:0xf bank_mask:0xf
	s_nop 1
	v_add_f32_dpp v188, v188, v188 row_ror:4 row_mask:0xf bank_mask:0xf
	v_add_f32_dpp v189, v189, v189 row_ror:4 row_mask:0xf bank_mask:0xf
	s_nop 1
	v_add_f32_dpp v188, v188, v188 row_ror:2 row_mask:0xf bank_mask:0xf
	v_add_f32_dpp v189, v189, v189 row_ror:2 row_mask:0xf bank_mask:0xf
	s_nop 1
	v_add_f32_dpp v188, v188, v188 row_ror:1 row_mask:0xf bank_mask:0xf
	v_add_f32_dpp v189, v189, v189 row_ror:1 row_mask:0xf bank_mask:0xf
	v_mov_b32_e32 v190, 0
	v_mov_b32_e32 v191, 0
	s_nop 0
	s_mov_b64 exec, s[18:19]
	global_store_dwordx4 v139, v[188:191], s[12:13]
	s_mov_b64 exec, -1
	s_mov_b32 s20, 0x10000
	s_movk_i32 s21, 0x1000
	s_add_u32 s10, s10, s20
	s_addc_u32 s11, s11, 0
	s_add_u32 s12, s12, s21
	s_addc_u32 s13, s13, 0
	s_waitcnt vmcnt(0)
	s_branch .LBB0_183
